# peeled first K-loop iteration in the five GEMM loops (first MFMA per accumulator takes C=0), removed the 128 v_mov zeroing per unit
# speedup vs baseline: 1.0031x; 1.0031x over previous
; #define PG8_STAGE(bufoff, gbase, voff) do { _Pragma("unroll") for (int _i = 0; _i < 2; ++_i) \
;         __builtin_amdgcn_global_load_lds((const unsigned*)((const char*)(gbase) + (voff)[_i]), (PG8_LAS unsigned*)(lds + (bufoff) + ldsw + _i * 8192), 16, 0, 0); } while (0)
; #define PG8_LDA(dst, b, h) do { _Pragma("unroll") for (int m = 0; m < 4; ++m) _Pragma("unroll") for (int k = 0; k < 2; ++k) dst[m][k] = *(const PG8_LAS bf16x8*)(lds + PG8_SA(b, h) + aoff + m * 2048 + k * 1024); } while (0)
; #define PG8_LDB(dst, b, h) do { _Pragma("unroll") for (int n = 0; n < 2; ++n) _Pragma("unroll") for (int k = 0; k < 2; ++k) dst[n][k] = *(const PG8_LAS bf16x8*)(lds + PG8_SB(b, h) + boff + n * 2048 + k * 1024); } while (0)
; template <class Epi, class Sched, bool ALIGN_EPI = false, bool SP2 = false>
; __device__ __forceinline__ void gemm_phase(PG8_LAS unsigned char* lds, const Gemm g, const Sched& S, const Epi& E) {
;     ...
;     f32x4 acc[2][2][4][2];
; #pragma unroll
;     for (int a = 0; a < 2; ++a)
; #pragma unroll
;         for (int b = 0; b < 2; ++b)
; #pragma unroll
;             for (int m = 0; m < 4; ++m)
; #pragma unroll
;                 for (int n = 0; n < 2; ++n) acc[a][b][m][n] = (f32x4){0.f, 0.f, 0.f, 0.f};
;     ...
;         const bool has_next = S.next(ui + 1, nxt);
;         const char* nA = has_next ? (const char*)g.A + (size_t)nxt.pm * tstep : cA; const char* nB = has_next ? (const char*)g.Bt + (size_t)nxt.pn * tstep : cB;
;         for (int t = 0; t < nt; t += 2) {
;             const bool last = (t == nt - 2);
;             const char* a1 = cA + (size_t)(t + 1) * kstep;
;             const char* a2 = last ? nA : cA + (size_t)(t + 2) * kstep; const char* b2 = last ? nB : cB + (size_t)(t + 2) * kstep;
;             const char* a3 = a2 + kstep; const char* b3 = b2 + kstep;
;             if (last && has_next) S.a_ready(nxt);
;             if constexpr (SP2) {
;             PG8_LDB(B0, 0, 0); PG8_LDB(B1, 0, 1); PG8_SCHED; PG8_LDA(At, 0, 0); PG8_STAGE(PG8_SA(1, 1), a1 + hstep, voffA);
;             PG8_WAIT_V(8); PG8_WAIT_L(0); PG8_BAR; PG8_MMA(0, 0, At, B0); PG8_MMA(0, 1, At, B1); PG8_BAR; PG8_SCHED;
;             PG8_LDA(At, 0, 1); PG8_STAGE(PG8_SB(0, 0), b2, voffB); PG8_STAGE(PG8_SB(0, 1), b2 + hstep, voffB); PG8_STAGE(PG8_SA(0, 0), a2, voffA);
;             PG8_WAIT_V(8); PG8_WAIT_L(0); PG8_BAR; PG8_MMA(1, 0, At, B0); PG8_MMA(1, 1, At, B1); PG8_BAR; PG8_SCHED;
.LBB0_127:
	s_ashr_i32 s47, s46, 31
	s_lshl_b64 s[50:51], s[46:47], 19
	s_add_u32 s50, s36, s50
	s_addc_u32 s51, s37, s51
	s_and_b64 s[54:55], s[2:3], exec
	s_cselect_b32 s47, s51, s59
	s_cselect_b32 s89, s50, s58
	s_ashr_i32 s41, s40, 31
	s_lshl_b64 s[54:55], s[40:41], 19
	s_add_u32 s54, s82, s54
	s_addc_u32 s55, s83, s55
	s_and_b64 s[62:63], s[2:3], exec
	s_cselect_b32 s41, s55, s61
	s_cselect_b32 s90, s54, s60
	s_add_u32 s58, s58, 0x40080
	s_addc_u32 s59, s59, 0
	s_add_u32 s91, s60, 0x100
	s_addc_u32 s92, s61, 0
	s_mov_b32 s93, -2
	ds_read_b128 v[160:163], v157
	ds_read_b128 v[164:167], v157 offset:1024
	ds_read_b128 v[168:171], v157 offset:2048
	ds_read_b128 v[172:175], v157 offset:3072
	ds_read_b128 v[176:179], v158
	ds_read_b128 v[180:183], v158 offset:1024
	ds_read_b128 v[184:187], v158 offset:2048
	ds_read_b128 v[188:191], v158 offset:3072
	s_add_u32 s19, s58, 0xfffc0080
	s_addc_u32 s60, s59, -1
	s_cmp_eq_u32 s93, 12
	s_cselect_b32 s63, s47, s60
	s_cselect_b32 s62, s89, s19
	s_cselect_b32 s61, s41, s92
	s_cselect_b32 s60, s90, s91
	v_lshl_add_u64 v[144:145], s[58:59], 0, v[136:137]
	s_add_i32 m0, s18, 0xc000
	ds_read_b128 v[192:195], v159
	ds_read_b128 v[196:199], v159 offset:1024
	ds_read_b128 v[200:203], v159 offset:2048
	ds_read_b128 v[208:211], v159 offset:3072
	ds_read_b128 v[212:215], v159 offset:4096
	ds_read_b128 v[216:219], v159 offset:5120
	ds_read_b128 v[220:223], v159 offset:6144
	ds_read_b128 v[224:227], v159 offset:7168
	global_load_lds_dwordx4 v[144:145], off
	v_lshl_add_u64 v[144:145], s[58:59], 0, v[138:139]
	s_add_i32 m0, s18, 0xe000
	s_nop 0
	global_load_lds_dwordx4 v[144:145], off
	s_waitcnt vmcnt(8)
	s_waitcnt lgkmcnt(0)
	s_barrier
	s_setprio 1
	s_waitcnt lgkmcnt(0)
	v_mfma_f32_16x16x32_bf16 v[124:127], v[160:163], v[192:195], 0
	v_mfma_f32_16x16x32_bf16 v[120:123], v[168:171], v[192:195], 0
	v_mfma_f32_16x16x32_bf16 v[112:115], v[160:163], v[200:203], 0
	v_mfma_f32_16x16x32_bf16 v[104:107], v[168:171], v[200:203], 0
	v_mfma_f32_16x16x32_bf16 v[96:99], v[160:163], v[212:215], 0
	v_mfma_f32_16x16x32_bf16 v[88:91], v[168:171], v[212:215], 0
	v_mfma_f32_16x16x32_bf16 v[80:83], v[160:163], v[220:223], 0
	v_mfma_f32_16x16x32_bf16 v[72:75], v[168:171], v[220:223], 0
	v_mfma_f32_16x16x32_bf16 v[124:127], v[164:167], v[196:199], v[124:127]
	v_mfma_f32_16x16x32_bf16 v[120:123], v[172:175], v[196:199], v[120:123]
	v_mfma_f32_16x16x32_bf16 v[112:115], v[164:167], v[208:211], v[112:115]
	v_mfma_f32_16x16x32_bf16 v[104:107], v[172:175], v[208:211], v[104:107]
	v_mfma_f32_16x16x32_bf16 v[96:99], v[164:167], v[216:219], v[96:99]
	v_mfma_f32_16x16x32_bf16 v[88:91], v[172:175], v[216:219], v[88:91]
	v_mfma_f32_16x16x32_bf16 v[80:83], v[164:167], v[224:227], v[80:83]
	v_mfma_f32_16x16x32_bf16 v[72:75], v[172:175], v[224:227], v[72:75]
	s_setprio 0
	s_setprio 1
	v_mfma_f32_16x16x32_bf16 v[116:119], v[176:179], v[192:195], 0
	v_mfma_f32_16x16x32_bf16 v[108:111], v[184:187], v[192:195], 0
	v_mfma_f32_16x16x32_bf16 v[100:103], v[176:179], v[200:203], 0
	v_mfma_f32_16x16x32_bf16 v[92:95], v[184:187], v[200:203], 0
	v_mfma_f32_16x16x32_bf16 v[84:87], v[176:179], v[212:215], 0
	v_mfma_f32_16x16x32_bf16 v[76:79], v[184:187], v[212:215], 0
	v_mfma_f32_16x16x32_bf16 v[68:71], v[176:179], v[220:223], 0
	v_mfma_f32_16x16x32_bf16 v[64:67], v[184:187], v[220:223], 0
	v_mfma_f32_16x16x32_bf16 v[116:119], v[180:183], v[196:199], v[116:119]
	v_mfma_f32_16x16x32_bf16 v[108:111], v[188:191], v[196:199], v[108:111]
	v_mfma_f32_16x16x32_bf16 v[100:103], v[180:183], v[208:211], v[100:103]
	v_mfma_f32_16x16x32_bf16 v[92:95], v[188:191], v[208:211], v[92:95]
	v_mfma_f32_16x16x32_bf16 v[84:87], v[180:183], v[216:219], v[84:87]
	v_mfma_f32_16x16x32_bf16 v[76:79], v[188:191], v[216:219], v[76:79]
	v_mfma_f32_16x16x32_bf16 v[68:71], v[180:183], v[224:227], v[68:71]
	v_mfma_f32_16x16x32_bf16 v[64:67], v[188:191], v[224:227], v[64:67]
	s_setprio 0
	s_barrier
	s_add_i32 s19, s75, s15
	v_lshl_add_u64 v[144:145], s[60:61], 0, v[130:131]
	s_mov_b32 m0, s19
	ds_read_b128 v[192:195], v159 offset:16384
	ds_read_b128 v[196:199], v159 offset:17408
	ds_read_b128 v[200:203], v159 offset:18432
	ds_read_b128 v[208:211], v159 offset:19456
	ds_read_b128 v[212:215], v159 offset:20480
	ds_read_b128 v[216:219], v159 offset:21504
	ds_read_b128 v[220:223], v159 offset:22528
	ds_read_b128 v[224:227], v159 offset:23552
	global_load_lds_dwordx4 v[144:145], off
	s_add_i32 m0, s19, 0x2000
	s_add_u32 s70, s60, 0x40000
	v_lshl_add_u64 v[204:205], s[60:61], 0, v[134:135]
	s_addc_u32 s71, s61, 0
	s_add_i32 s19, s84, s15
	global_load_lds_dwordx4 v[204:205], off
	v_lshl_add_u64 v[228:229], s[70:71], 0, v[130:131]
	s_mov_b32 m0, s19
	v_lshl_add_u64 v[230:231], s[62:63], 0, v[132:133]
	global_load_lds_dwordx4 v[228:229], off
	v_lshl_add_u64 v[228:229], s[70:71], 0, v[134:135]
	s_add_i32 m0, s19, 0x2000
	s_nop 0
	global_load_lds_dwordx4 v[228:229], off
	v_lshl_add_u64 v[228:229], s[62:63], 0, v[128:129]
	s_mov_b32 m0, s18
	s_nop 0
	global_load_lds_dwordx4 v[228:229], off
	s_mov_b32 m0, s23
	s_nop 0
	global_load_lds_dwordx4 v[230:231], off
	s_waitcnt vmcnt(8)
	s_waitcnt lgkmcnt(0)
	s_barrier
; #define PG8_STAGE(bufoff, gbase, voff) do { _Pragma("unroll") for (int _i = 0; _i < 2; ++_i) \
;         __builtin_amdgcn_global_load_lds((const unsigned*)((const char*)(gbase) + (voff)[_i]), (PG8_LAS unsigned*)(lds + (bufoff) + ldsw + _i * 8192), 16, 0, 0); } while (0)
; #define PG8_LDA(dst, b, h) do { _Pragma("unroll") for (int m = 0; m < 4; ++m) _Pragma("unroll") for (int k = 0; k < 2; ++k) dst[m][k] = *(const PG8_LAS bf16x8*)(lds + PG8_SA(b, h) + aoff + m * 2048 + k * 1024); } while (0)
; #define PG8_LDB(dst, b, h) do { _Pragma("unroll") for (int n = 0; n < 2; ++n) _Pragma("unroll") for (int k = 0; k < 2; ++k) dst[n][k] = *(const PG8_LAS bf16x8*)(lds + PG8_SB(b, h) + boff + n * 2048 + k * 1024); } while (0)
; #define PG8_MMA(ai, bj, At, Bt) do { __builtin_amdgcn_s_setprio(1); _Pragma("unroll") for (int m = 0; m < 4; ++m) _Pragma("unroll") for (int n = 0; n < 2; ++n) _Pragma("unroll") for (int k = 0; k < 2; ++k) \
;         acc[ai][bj][m][n] = __builtin_amdgcn_mfma_f32_16x16x32_bf16(Bt[n][k], At[m][k], acc[ai][bj][m][n], 0, 0, 0); __builtin_amdgcn_s_setprio(0); } while (0)
; #define PG8_WAIT_V(n) asm volatile("s_waitcnt vmcnt(" #n ")" ::: "memory")
; #define PG8_WAIT_L(n) asm volatile("s_waitcnt lgkmcnt(" #n ")" ::: "memory")
; #define PG8_BAR __builtin_amdgcn_s_barrier()
; #define PG8_SCHED __builtin_amdgcn_sched_barrier(0)
; template <class Epi, class Sched, bool ALIGN_EPI = false, bool SP2 = false>
; __device__ __forceinline__ void gemm_phase(PG8_LAS unsigned char* lds, const Gemm g, const Sched& S, const Epi& E) {
;     ...
;             PG8_WAIT_V(8); PG8_WAIT_L(0); PG8_BAR; PG8_MMA(1, 0, At, B0); PG8_MMA(1, 1, At, B1); PG8_BAR; PG8_SCHED;
;             PG8_LDB(B0, 1, 0); PG8_LDB(B1, 1, 1); PG8_SCHED; PG8_LDA(At, 1, 0); PG8_STAGE(PG8_SA(0, 1), a2 + hstep, voffA);
;             PG8_WAIT_V(8); PG8_WAIT_L(0); PG8_BAR; PG8_MMA(0, 0, At, B0); PG8_MMA(0, 1, At, B1); PG8_BAR; PG8_SCHED;
	s_setprio 1
	s_waitcnt lgkmcnt(0)
	v_mfma_f32_16x16x32_bf16 v[60:63], v[160:163], v[192:195], 0
	v_mfma_f32_16x16x32_bf16 v[56:59], v[168:171], v[192:195], 0
	v_mfma_f32_16x16x32_bf16 v[48:51], v[160:163], v[200:203], 0
	v_mfma_f32_16x16x32_bf16 v[40:43], v[168:171], v[200:203], 0
	v_mfma_f32_16x16x32_bf16 v[32:35], v[160:163], v[212:215], 0
	v_mfma_f32_16x16x32_bf16 v[24:27], v[168:171], v[212:215], 0
	v_mfma_f32_16x16x32_bf16 v[16:19], v[160:163], v[220:223], 0
	v_mfma_f32_16x16x32_bf16 v[8:11], v[168:171], v[220:223], 0
	v_mfma_f32_16x16x32_bf16 v[60:63], v[164:167], v[196:199], v[60:63]
	v_mfma_f32_16x16x32_bf16 v[56:59], v[172:175], v[196:199], v[56:59]
	v_mfma_f32_16x16x32_bf16 v[48:51], v[164:167], v[208:211], v[48:51]
	v_mfma_f32_16x16x32_bf16 v[40:43], v[172:175], v[208:211], v[40:43]
	v_mfma_f32_16x16x32_bf16 v[32:35], v[164:167], v[216:219], v[32:35]
	v_mfma_f32_16x16x32_bf16 v[24:27], v[172:175], v[216:219], v[24:27]
	v_mfma_f32_16x16x32_bf16 v[16:19], v[164:167], v[224:227], v[16:19]
	v_mfma_f32_16x16x32_bf16 v[8:11], v[172:175], v[224:227], v[8:11]
	s_setprio 0
	s_setprio 1
	v_mfma_f32_16x16x32_bf16 v[52:55], v[176:179], v[192:195], 0
	v_mfma_f32_16x16x32_bf16 v[44:47], v[184:187], v[192:195], 0
	v_mfma_f32_16x16x32_bf16 v[36:39], v[176:179], v[200:203], 0
	v_mfma_f32_16x16x32_bf16 v[28:31], v[184:187], v[200:203], 0
	v_mfma_f32_16x16x32_bf16 v[20:23], v[176:179], v[212:215], 0
	v_mfma_f32_16x16x32_bf16 v[12:15], v[184:187], v[212:215], 0
	v_mfma_f32_16x16x32_bf16 v[4:7], v[176:179], v[220:223], 0
	v_mfma_f32_16x16x32_bf16 v[0:3], v[184:187], v[220:223], 0
	v_mfma_f32_16x16x32_bf16 v[52:55], v[180:183], v[196:199], v[52:55]
	v_mfma_f32_16x16x32_bf16 v[44:47], v[188:191], v[196:199], v[44:47]
	v_mfma_f32_16x16x32_bf16 v[36:39], v[180:183], v[208:211], v[36:39]
	v_mfma_f32_16x16x32_bf16 v[28:31], v[188:191], v[208:211], v[28:31]
	v_mfma_f32_16x16x32_bf16 v[20:23], v[180:183], v[216:219], v[20:23]
	v_mfma_f32_16x16x32_bf16 v[12:15], v[188:191], v[216:219], v[12:15]
	v_mfma_f32_16x16x32_bf16 v[4:7], v[180:183], v[224:227], v[4:7]
	v_mfma_f32_16x16x32_bf16 v[0:3], v[188:191], v[224:227], v[0:3]
	s_setprio 0
	s_barrier
	s_add_i32 s19, 0, 0x18000
	s_add_i32 s70, 0, 0x1c000
	v_add_u32_e32 v172, s19, v155
	v_add_u32_e32 v188, s70, v155
	ds_read_b128 v[160:163], v172
	ds_read_b128 v[164:167], v172 offset:1024
	ds_read_b128 v[168:171], v172 offset:2048
	ds_read_b128 v[172:175], v172 offset:3072
	ds_read_b128 v[176:179], v188
	ds_read_b128 v[180:183], v188 offset:1024
	ds_read_b128 v[184:187], v188 offset:2048
	ds_read_b128 v[188:191], v188 offset:3072
	s_add_u32 s62, s62, 0x40000
	s_addc_u32 s63, s63, 0
	s_mov_b32 m0, s33
	v_lshl_add_u64 v[232:233], s[62:63], 0, v[128:129]
	ds_read_b128 v[192:195], v159 offset:32768
	ds_read_b128 v[196:199], v159 offset:33792
	ds_read_b128 v[200:203], v159 offset:34816
	ds_read_b128 v[208:211], v159 offset:35840
	ds_read_b128 v[212:215], v159 offset:36864
	ds_read_b128 v[216:219], v159 offset:37888
	ds_read_b128 v[220:223], v159 offset:38912
	ds_read_b128 v[224:227], v159 offset:39936
	global_load_lds_dwordx4 v[232:233], off
	v_lshl_add_u64 v[232:233], s[62:63], 0, v[132:133]
	s_mov_b32 m0, s35
	s_nop 0
	global_load_lds_dwordx4 v[232:233], off
	s_waitcnt vmcnt(8)
	s_waitcnt lgkmcnt(0)
	s_barrier
	s_setprio 1
	s_waitcnt lgkmcnt(0)
	v_mfma_f32_16x16x32_bf16 v[124:127], v[160:163], v[192:195], v[124:127]
	v_mfma_f32_16x16x32_bf16 v[120:123], v[168:171], v[192:195], v[120:123]
	v_mfma_f32_16x16x32_bf16 v[112:115], v[160:163], v[200:203], v[112:115]
	v_mfma_f32_16x16x32_bf16 v[104:107], v[168:171], v[200:203], v[104:107]
	v_mfma_f32_16x16x32_bf16 v[96:99], v[160:163], v[212:215], v[96:99]
	v_mfma_f32_16x16x32_bf16 v[88:91], v[168:171], v[212:215], v[88:91]
	v_mfma_f32_16x16x32_bf16 v[80:83], v[160:163], v[220:223], v[80:83]
	v_mfma_f32_16x16x32_bf16 v[72:75], v[168:171], v[220:223], v[72:75]
	v_mfma_f32_16x16x32_bf16 v[124:127], v[164:167], v[196:199], v[124:127]
	v_mfma_f32_16x16x32_bf16 v[120:123], v[172:175], v[196:199], v[120:123]
	v_mfma_f32_16x16x32_bf16 v[112:115], v[164:167], v[208:211], v[112:115]
	v_mfma_f32_16x16x32_bf16 v[104:107], v[172:175], v[208:211], v[104:107]
	v_mfma_f32_16x16x32_bf16 v[96:99], v[164:167], v[216:219], v[96:99]
	v_mfma_f32_16x16x32_bf16 v[88:91], v[172:175], v[216:219], v[88:91]
	v_mfma_f32_16x16x32_bf16 v[80:83], v[164:167], v[224:227], v[80:83]
	v_mfma_f32_16x16x32_bf16 v[72:75], v[172:175], v[224:227], v[72:75]
	s_setprio 0
	s_setprio 1
	v_mfma_f32_16x16x32_bf16 v[116:119], v[176:179], v[192:195], v[116:119]
	v_mfma_f32_16x16x32_bf16 v[108:111], v[184:187], v[192:195], v[108:111]
	v_mfma_f32_16x16x32_bf16 v[100:103], v[176:179], v[200:203], v[100:103]
	v_mfma_f32_16x16x32_bf16 v[92:95], v[184:187], v[200:203], v[92:95]
	v_mfma_f32_16x16x32_bf16 v[84:87], v[176:179], v[212:215], v[84:87]
	v_mfma_f32_16x16x32_bf16 v[76:79], v[184:187], v[212:215], v[76:79]
	v_mfma_f32_16x16x32_bf16 v[68:71], v[176:179], v[220:223], v[68:71]
	v_mfma_f32_16x16x32_bf16 v[64:67], v[184:187], v[220:223], v[64:67]
	v_mfma_f32_16x16x32_bf16 v[116:119], v[180:183], v[196:199], v[116:119]
	v_mfma_f32_16x16x32_bf16 v[108:111], v[188:191], v[196:199], v[108:111]
	v_mfma_f32_16x16x32_bf16 v[100:103], v[180:183], v[208:211], v[100:103]
	v_mfma_f32_16x16x32_bf16 v[92:95], v[188:191], v[208:211], v[92:95]
	v_mfma_f32_16x16x32_bf16 v[84:87], v[180:183], v[216:219], v[84:87]
	v_mfma_f32_16x16x32_bf16 v[76:79], v[188:191], v[216:219], v[76:79]
	v_mfma_f32_16x16x32_bf16 v[68:71], v[180:183], v[224:227], v[68:71]
	v_mfma_f32_16x16x32_bf16 v[64:67], v[188:191], v[224:227], v[64:67]
	s_setprio 0
	s_barrier
; #define PG8_STAGE(bufoff, gbase, voff) do { _Pragma("unroll") for (int _i = 0; _i < 2; ++_i) \
;         __builtin_amdgcn_global_load_lds((const unsigned*)((const char*)(gbase) + (voff)[_i]), (PG8_LAS unsigned*)(lds + (bufoff) + ldsw + _i * 8192), 16, 0, 0); } while (0)
; #define PG8_LDA(dst, b, h) do { _Pragma("unroll") for (int m = 0; m < 4; ++m) _Pragma("unroll") for (int k = 0; k < 2; ++k) dst[m][k] = *(const PG8_LAS bf16x8*)(lds + PG8_SA(b, h) + aoff + m * 2048 + k * 1024); } while (0)
; #define PG8_MMA(ai, bj, At, Bt) do { __builtin_amdgcn_s_setprio(1); _Pragma("unroll") for (int m = 0; m < 4; ++m) _Pragma("unroll") for (int n = 0; n < 2; ++n) _Pragma("unroll") for (int k = 0; k < 2; ++k) \
;         acc[ai][bj][m][n] = __builtin_amdgcn_mfma_f32_16x16x32_bf16(Bt[n][k], At[m][k], acc[ai][bj][m][n], 0, 0, 0); __builtin_amdgcn_s_setprio(0); } while (0)
; #define PG8_WAIT_V(n) asm volatile("s_waitcnt vmcnt(" #n ")" ::: "memory")
; #define PG8_WAIT_L(n) asm volatile("s_waitcnt lgkmcnt(" #n ")" ::: "memory")
; #define PG8_BAR __builtin_amdgcn_s_barrier()
; #define PG8_SCHED __builtin_amdgcn_sched_barrier(0)
; template <class Epi, class Sched, bool ALIGN_EPI = false, bool SP2 = false>
; __device__ __forceinline__ void gemm_phase(PG8_LAS unsigned char* lds, const Gemm g, const Sched& S, const Epi& E) {
;     ...
;         for (int t = 0; t < nt; t += 2) {
;             const bool last = (t == nt - 2);
;     ...
;             PG8_LDA(At, 1, 1); PG8_STAGE(PG8_SB(1, 0), b3, voffB); PG8_STAGE(PG8_SB(1, 1), b3 + hstep, voffB); PG8_STAGE(PG8_SA(1, 0), a3, voffA);
;             PG8_WAIT_V(8); PG8_WAIT_L(0); PG8_BAR; PG8_MMA(1, 0, At, B0); PG8_MMA(1, 1, At, B1); PG8_BAR; PG8_SCHED;
	s_add_i32 s19, s19, s15
	v_lshl_add_u64 v[144:145], v[144:145], 0, s[8:9]
	s_mov_b32 m0, s19
	ds_read_b128 v[192:195], v159 offset:49152
	ds_read_b128 v[196:199], v159 offset:50176
	ds_read_b128 v[200:203], v159 offset:51200
	ds_read_b128 v[208:211], v159 offset:52224
	ds_read_b128 v[212:215], v159 offset:53248
	ds_read_b128 v[216:219], v159 offset:54272
	ds_read_b128 v[220:223], v159 offset:55296
	ds_read_b128 v[224:227], v159 offset:56320
	global_load_lds_dwordx4 v[144:145], off
	s_add_i32 m0, s19, 0x2000
	s_add_u32 s60, s60, 0x40080
	v_lshl_add_u64 v[144:145], v[204:205], 0, s[8:9]
	s_addc_u32 s61, s61, 0
	s_add_i32 s19, s70, s15
	global_load_lds_dwordx4 v[144:145], off
	v_lshl_add_u64 v[144:145], s[60:61], 0, v[130:131]
	s_mov_b32 m0, s19
	s_nop 0
	global_load_lds_dwordx4 v[144:145], off
	v_lshl_add_u64 v[144:145], s[60:61], 0, v[134:135]
	s_add_i32 m0, s19, 0x2000
	s_nop 0
	global_load_lds_dwordx4 v[144:145], off
	v_lshl_add_u64 v[144:145], v[228:229], 0, s[8:9]
	s_mov_b32 m0, s64
	s_nop 0
	global_load_lds_dwordx4 v[144:145], off
	v_lshl_add_u64 v[144:145], v[230:231], 0, s[8:9]
	s_mov_b32 m0, s65
	s_nop 0
	global_load_lds_dwordx4 v[144:145], off
	s_waitcnt vmcnt(8)
	s_waitcnt lgkmcnt(0)
	s_barrier
	s_setprio 1
	s_waitcnt lgkmcnt(0)
	v_mfma_f32_16x16x32_bf16 v[60:63], v[160:163], v[192:195], v[60:63]
	v_mfma_f32_16x16x32_bf16 v[56:59], v[168:171], v[192:195], v[56:59]
	v_mfma_f32_16x16x32_bf16 v[48:51], v[160:163], v[200:203], v[48:51]
	v_mfma_f32_16x16x32_bf16 v[40:43], v[168:171], v[200:203], v[40:43]
	v_mfma_f32_16x16x32_bf16 v[32:35], v[160:163], v[212:215], v[32:35]
	v_mfma_f32_16x16x32_bf16 v[24:27], v[168:171], v[212:215], v[24:27]
	v_mfma_f32_16x16x32_bf16 v[16:19], v[160:163], v[220:223], v[16:19]
	v_mfma_f32_16x16x32_bf16 v[8:11], v[168:171], v[220:223], v[8:11]
	v_mfma_f32_16x16x32_bf16 v[60:63], v[164:167], v[196:199], v[60:63]
	v_mfma_f32_16x16x32_bf16 v[56:59], v[172:175], v[196:199], v[56:59]
	v_mfma_f32_16x16x32_bf16 v[48:51], v[164:167], v[208:211], v[48:51]
	v_mfma_f32_16x16x32_bf16 v[40:43], v[172:175], v[208:211], v[40:43]
	v_mfma_f32_16x16x32_bf16 v[32:35], v[164:167], v[216:219], v[32:35]
	v_mfma_f32_16x16x32_bf16 v[24:27], v[172:175], v[216:219], v[24:27]
	v_mfma_f32_16x16x32_bf16 v[16:19], v[164:167], v[224:227], v[16:19]
	v_mfma_f32_16x16x32_bf16 v[8:11], v[172:175], v[224:227], v[8:11]
	s_setprio 0
	s_setprio 1
	v_mfma_f32_16x16x32_bf16 v[52:55], v[176:179], v[192:195], v[52:55]
	v_mfma_f32_16x16x32_bf16 v[44:47], v[184:187], v[192:195], v[44:47]
	v_mfma_f32_16x16x32_bf16 v[36:39], v[176:179], v[200:203], v[36:39]
	v_mfma_f32_16x16x32_bf16 v[28:31], v[184:187], v[200:203], v[28:31]
	v_mfma_f32_16x16x32_bf16 v[20:23], v[176:179], v[212:215], v[20:23]
	v_mfma_f32_16x16x32_bf16 v[12:15], v[184:187], v[212:215], v[12:15]
	v_mfma_f32_16x16x32_bf16 v[4:7], v[176:179], v[220:223], v[4:7]
	v_mfma_f32_16x16x32_bf16 v[0:3], v[184:187], v[220:223], v[0:3]
	v_mfma_f32_16x16x32_bf16 v[52:55], v[180:183], v[196:199], v[52:55]
	v_mfma_f32_16x16x32_bf16 v[44:47], v[188:191], v[196:199], v[44:47]
	v_mfma_f32_16x16x32_bf16 v[36:39], v[180:183], v[208:211], v[36:39]
	v_mfma_f32_16x16x32_bf16 v[28:31], v[188:191], v[208:211], v[28:31]
	v_mfma_f32_16x16x32_bf16 v[20:23], v[180:183], v[216:219], v[20:23]
	v_mfma_f32_16x16x32_bf16 v[12:15], v[188:191], v[216:219], v[12:15]
	v_mfma_f32_16x16x32_bf16 v[4:7], v[180:183], v[224:227], v[4:7]
	v_mfma_f32_16x16x32_bf16 v[0:3], v[188:191], v[224:227], v[0:3]
	s_setprio 0
	s_barrier
	s_add_i32 s93, s93, 2
	s_add_u32 s58, s58, 0x100
	s_addc_u32 s59, s59, 0
	s_add_u32 s91, s91, 0x100
	s_addc_u32 s92, s92, 0
	s_cmp_gt_u32 s93, 13
	s_cbranch_scc1 .Lpeel_exit_0

; #define PG8_BAR __builtin_amdgcn_s_barrier()
; template <class Epi, class Sched, bool ALIGN_EPI = false, bool SP2 = false>
; __device__ __forceinline__ void gemm_phase(PG8_LAS unsigned char* lds, const Gemm g, const Sched& S, const Epi& E) {
;     ...
;         if constexpr (ALIGN_EPI) { if (wr == 0) PG8_BAR; }
.Lpeel_exit_0:
	s_and_b64 vcc, exec, s[10:11]
	s_cbranch_vccz .LBB0_131
	s_barrier

; #define PG8_STAGE(bufoff, gbase, voff) do { _Pragma("unroll") for (int _i = 0; _i < 2; ++_i) \
;         __builtin_amdgcn_global_load_lds((const unsigned*)((const char*)(gbase) + (voff)[_i]), (PG8_LAS unsigned*)(lds + (bufoff) + ldsw + _i * 8192), 16, 0, 0); } while (0)
; #define PG8_LDA(dst, b, h) do { _Pragma("unroll") for (int m = 0; m < 4; ++m) _Pragma("unroll") for (int k = 0; k < 2; ++k) dst[m][k] = *(const PG8_LAS bf16x8*)(lds + PG8_SA(b, h) + aoff + m * 2048 + k * 1024); } while (0)
; #define PG8_LDB(dst, b, h) do { _Pragma("unroll") for (int n = 0; n < 2; ++n) _Pragma("unroll") for (int k = 0; k < 2; ++k) dst[n][k] = *(const PG8_LAS bf16x8*)(lds + PG8_SB(b, h) + boff + n * 2048 + k * 1024); } while (0)
; template <class Epi, class Sched, bool ALIGN_EPI = false, bool SP2 = false>
; __device__ __forceinline__ void gemm_phase(PG8_LAS unsigned char* lds, const Gemm g, const Sched& S, const Epi& E) {
;     ...
;     f32x4 acc[2][2][4][2];
; #pragma unroll
;     for (int a = 0; a < 2; ++a)
; #pragma unroll
;         for (int b = 0; b < 2; ++b)
; #pragma unroll
;             for (int m = 0; m < 4; ++m)
; #pragma unroll
;                 for (int n = 0; n < 2; ++n) acc[a][b][m][n] = (f32x4){0.f, 0.f, 0.f, 0.f};
;     ...
;         const bool has_next = S.next(ui + 1, nxt);
;         const char* nA = has_next ? (const char*)g.A + (size_t)nxt.pm * tstep : cA; const char* nB = has_next ? (const char*)g.Bt + (size_t)nxt.pn * tstep : cB;
;         for (int t = 0; t < nt; t += 2) {
;             const bool last = (t == nt - 2);
;             const char* a1 = cA + (size_t)(t + 1) * kstep;
;             const char* a2 = last ? nA : cA + (size_t)(t + 2) * kstep; const char* b2 = last ? nB : cB + (size_t)(t + 2) * kstep;
;             const char* a3 = a2 + kstep; const char* b3 = b2 + kstep;
;             if (last && has_next) S.a_ready(nxt);
;             if constexpr (SP2) {
;             PG8_LDB(B0, 0, 0); PG8_LDB(B1, 0, 1); PG8_SCHED; PG8_LDA(At, 0, 0); PG8_STAGE(PG8_SA(1, 1), a1 + hstep, voffA);
;             PG8_WAIT_V(8); PG8_WAIT_L(0); PG8_BAR; PG8_MMA(0, 0, At, B0); PG8_MMA(0, 1, At, B1); PG8_BAR; PG8_SCHED;
;             PG8_LDA(At, 0, 1); PG8_STAGE(PG8_SB(0, 0), b2, voffB); PG8_STAGE(PG8_SB(0, 1), b2 + hstep, voffB); PG8_STAGE(PG8_SA(0, 0), a2, voffA);
;             PG8_WAIT_V(8); PG8_WAIT_L(0); PG8_BAR; PG8_MMA(1, 0, At, B0); PG8_MMA(1, 1, At, B1); PG8_BAR; PG8_SCHED;
.LBB0_151:
	s_ashr_i32 s47, s46, 31
	s_lshl_b64 s[50:51], s[46:47], 19
	s_add_u32 s50, s15, s50
	s_addc_u32 s51, s18, s51
	s_and_b64 s[54:55], s[2:3], exec
	s_cselect_b32 s47, s51, s59
	s_cselect_b32 s89, s50, s58
	s_ashr_i32 s41, s40, 31
	s_lshl_b64 s[54:55], s[40:41], 19
	s_add_u32 s54, s36, s54
	s_addc_u32 s55, s37, s55
	s_and_b64 s[62:63], s[2:3], exec
	s_cselect_b32 s41, s55, s61
	s_cselect_b32 s90, s54, s60
	s_add_u32 s58, s58, 0x40080
	s_addc_u32 s59, s59, 0
	s_add_u32 s91, s60, 0x100
	s_addc_u32 s92, s61, 0
	s_mov_b32 s93, -2
	ds_read_b128 v[156:159], v146
	ds_read_b128 v[160:163], v146 offset:1024
	ds_read_b128 v[164:167], v146 offset:2048
	ds_read_b128 v[168:171], v146 offset:3072
	ds_read_b128 v[172:175], v147
	ds_read_b128 v[176:179], v147 offset:1024
	ds_read_b128 v[180:183], v147 offset:2048
	ds_read_b128 v[184:187], v147 offset:3072
	s_add_u32 s19, s58, 0xfffc0080
	s_addc_u32 s60, s59, -1
	s_cmp_eq_u32 s93, 12
	s_cselect_b32 s63, s47, s60
	s_cselect_b32 s62, s89, s19
	s_cselect_b32 s61, s41, s92
	s_cselect_b32 s60, s90, s91
	v_lshl_add_u64 v[144:145], s[58:59], 0, v[136:137]
	s_add_i32 m0, s33, 0xc000
	ds_read_b128 v[188:191], v148
	ds_read_b128 v[192:195], v148 offset:1024
	ds_read_b128 v[196:199], v148 offset:2048
	ds_read_b128 v[200:203], v148 offset:3072
	ds_read_b128 v[208:211], v148 offset:4096
	ds_read_b128 v[212:215], v148 offset:5120
	ds_read_b128 v[216:219], v148 offset:6144
	ds_read_b128 v[220:223], v148 offset:7168
	global_load_lds_dwordx4 v[144:145], off
	v_lshl_add_u64 v[144:145], s[58:59], 0, v[138:139]
	s_add_i32 m0, s33, 0xe000
	s_nop 0
	global_load_lds_dwordx4 v[144:145], off
	s_waitcnt vmcnt(8)
	s_waitcnt lgkmcnt(0)
	s_barrier
	s_setprio 1
	s_waitcnt lgkmcnt(0)
	v_mfma_f32_16x16x32_bf16 v[124:127], v[156:159], v[188:191], 0
	v_mfma_f32_16x16x32_bf16 v[120:123], v[164:167], v[188:191], 0
	v_mfma_f32_16x16x32_bf16 v[112:115], v[156:159], v[196:199], 0
	v_mfma_f32_16x16x32_bf16 v[104:107], v[164:167], v[196:199], 0
	v_mfma_f32_16x16x32_bf16 v[96:99], v[156:159], v[208:211], 0
	v_mfma_f32_16x16x32_bf16 v[88:91], v[164:167], v[208:211], 0
	v_mfma_f32_16x16x32_bf16 v[80:83], v[156:159], v[216:219], 0
	v_mfma_f32_16x16x32_bf16 v[72:75], v[164:167], v[216:219], 0
	v_mfma_f32_16x16x32_bf16 v[124:127], v[160:163], v[192:195], v[124:127]
	v_mfma_f32_16x16x32_bf16 v[120:123], v[168:171], v[192:195], v[120:123]
	v_mfma_f32_16x16x32_bf16 v[112:115], v[160:163], v[200:203], v[112:115]
	v_mfma_f32_16x16x32_bf16 v[104:107], v[168:171], v[200:203], v[104:107]
	v_mfma_f32_16x16x32_bf16 v[96:99], v[160:163], v[212:215], v[96:99]
	v_mfma_f32_16x16x32_bf16 v[88:91], v[168:171], v[212:215], v[88:91]
	v_mfma_f32_16x16x32_bf16 v[80:83], v[160:163], v[220:223], v[80:83]
	v_mfma_f32_16x16x32_bf16 v[72:75], v[168:171], v[220:223], v[72:75]
	s_setprio 0
	s_setprio 1
	v_mfma_f32_16x16x32_bf16 v[116:119], v[172:175], v[188:191], 0
	v_mfma_f32_16x16x32_bf16 v[108:111], v[180:183], v[188:191], 0
	v_mfma_f32_16x16x32_bf16 v[100:103], v[172:175], v[196:199], 0
	v_mfma_f32_16x16x32_bf16 v[92:95], v[180:183], v[196:199], 0
	v_mfma_f32_16x16x32_bf16 v[84:87], v[172:175], v[208:211], 0
	v_mfma_f32_16x16x32_bf16 v[76:79], v[180:183], v[208:211], 0
	v_mfma_f32_16x16x32_bf16 v[68:71], v[172:175], v[216:219], 0
	v_mfma_f32_16x16x32_bf16 v[64:67], v[180:183], v[216:219], 0
	v_mfma_f32_16x16x32_bf16 v[116:119], v[176:179], v[192:195], v[116:119]
	v_mfma_f32_16x16x32_bf16 v[108:111], v[184:187], v[192:195], v[108:111]
	v_mfma_f32_16x16x32_bf16 v[100:103], v[176:179], v[200:203], v[100:103]
	v_mfma_f32_16x16x32_bf16 v[92:95], v[184:187], v[200:203], v[92:95]
	v_mfma_f32_16x16x32_bf16 v[84:87], v[176:179], v[212:215], v[84:87]
	v_mfma_f32_16x16x32_bf16 v[76:79], v[184:187], v[212:215], v[76:79]
	v_mfma_f32_16x16x32_bf16 v[68:71], v[176:179], v[220:223], v[68:71]
	v_mfma_f32_16x16x32_bf16 v[64:67], v[184:187], v[220:223], v[64:67]
	s_setprio 0
	s_barrier
	s_add_i32 s19, s83, s23
	v_lshl_add_u64 v[144:145], s[60:61], 0, v[130:131]
	s_mov_b32 m0, s19
	ds_read_b128 v[188:191], v148 offset:16384
	ds_read_b128 v[192:195], v148 offset:17408
	ds_read_b128 v[196:199], v148 offset:18432
	ds_read_b128 v[200:203], v148 offset:19456
	ds_read_b128 v[208:211], v148 offset:20480
	ds_read_b128 v[212:215], v148 offset:21504
	ds_read_b128 v[216:219], v148 offset:22528
	ds_read_b128 v[220:223], v148 offset:23552
	global_load_lds_dwordx4 v[144:145], off
	s_add_i32 m0, s19, 0x2000
	s_add_u32 s70, s60, 0x40000
	v_lshl_add_u64 v[152:153], s[60:61], 0, v[134:135]
	s_addc_u32 s71, s61, 0
	s_add_i32 s19, s84, s23
	global_load_lds_dwordx4 v[152:153], off
	v_lshl_add_u64 v[204:205], s[70:71], 0, v[130:131]
	s_mov_b32 m0, s19
	v_lshl_add_u64 v[224:225], s[62:63], 0, v[132:133]
	global_load_lds_dwordx4 v[204:205], off
	v_lshl_add_u64 v[204:205], s[70:71], 0, v[134:135]
	s_add_i32 m0, s19, 0x2000
	s_nop 0
	global_load_lds_dwordx4 v[204:205], off
	v_lshl_add_u64 v[204:205], s[62:63], 0, v[128:129]
	s_mov_b32 m0, s33
	s_nop 0
	global_load_lds_dwordx4 v[204:205], off
	s_mov_b32 m0, s35
	s_nop 0
	global_load_lds_dwordx4 v[224:225], off
	s_waitcnt vmcnt(8)
	s_waitcnt lgkmcnt(0)
	s_barrier
; #define PG8_STAGE(bufoff, gbase, voff) do { _Pragma("unroll") for (int _i = 0; _i < 2; ++_i) \
;         __builtin_amdgcn_global_load_lds((const unsigned*)((const char*)(gbase) + (voff)[_i]), (PG8_LAS unsigned*)(lds + (bufoff) + ldsw + _i * 8192), 16, 0, 0); } while (0)
; #define PG8_LDA(dst, b, h) do { _Pragma("unroll") for (int m = 0; m < 4; ++m) _Pragma("unroll") for (int k = 0; k < 2; ++k) dst[m][k] = *(const PG8_LAS bf16x8*)(lds + PG8_SA(b, h) + aoff + m * 2048 + k * 1024); } while (0)
; #define PG8_LDB(dst, b, h) do { _Pragma("unroll") for (int n = 0; n < 2; ++n) _Pragma("unroll") for (int k = 0; k < 2; ++k) dst[n][k] = *(const PG8_LAS bf16x8*)(lds + PG8_SB(b, h) + boff + n * 2048 + k * 1024); } while (0)
; #define PG8_MMA(ai, bj, At, Bt) do { __builtin_amdgcn_s_setprio(1); _Pragma("unroll") for (int m = 0; m < 4; ++m) _Pragma("unroll") for (int n = 0; n < 2; ++n) _Pragma("unroll") for (int k = 0; k < 2; ++k) \
;         acc[ai][bj][m][n] = __builtin_amdgcn_mfma_f32_16x16x32_bf16(Bt[n][k], At[m][k], acc[ai][bj][m][n], 0, 0, 0); __builtin_amdgcn_s_setprio(0); } while (0)
; #define PG8_WAIT_V(n) asm volatile("s_waitcnt vmcnt(" #n ")" ::: "memory")
; #define PG8_WAIT_L(n) asm volatile("s_waitcnt lgkmcnt(" #n ")" ::: "memory")
; #define PG8_BAR __builtin_amdgcn_s_barrier()
; #define PG8_SCHED __builtin_amdgcn_sched_barrier(0)
; template <class Epi, class Sched, bool ALIGN_EPI = false, bool SP2 = false>
; __device__ __forceinline__ void gemm_phase(PG8_LAS unsigned char* lds, const Gemm g, const Sched& S, const Epi& E) {
;     ...
;             PG8_WAIT_V(8); PG8_WAIT_L(0); PG8_BAR; PG8_MMA(1, 0, At, B0); PG8_MMA(1, 1, At, B1); PG8_BAR; PG8_SCHED;
;             PG8_LDB(B0, 1, 0); PG8_LDB(B1, 1, 1); PG8_SCHED; PG8_LDA(At, 1, 0); PG8_STAGE(PG8_SA(0, 1), a2 + hstep, voffA);
;             PG8_WAIT_V(8); PG8_WAIT_L(0); PG8_BAR; PG8_MMA(0, 0, At, B0); PG8_MMA(0, 1, At, B1); PG8_BAR; PG8_SCHED;
	s_setprio 1
	s_waitcnt lgkmcnt(0)
	v_mfma_f32_16x16x32_bf16 v[60:63], v[156:159], v[188:191], 0
	v_mfma_f32_16x16x32_bf16 v[56:59], v[164:167], v[188:191], 0
	v_mfma_f32_16x16x32_bf16 v[48:51], v[156:159], v[196:199], 0
	v_mfma_f32_16x16x32_bf16 v[40:43], v[164:167], v[196:199], 0
	v_mfma_f32_16x16x32_bf16 v[32:35], v[156:159], v[208:211], 0
	v_mfma_f32_16x16x32_bf16 v[24:27], v[164:167], v[208:211], 0
	v_mfma_f32_16x16x32_bf16 v[16:19], v[156:159], v[216:219], 0
	v_mfma_f32_16x16x32_bf16 v[8:11], v[164:167], v[216:219], 0
	v_mfma_f32_16x16x32_bf16 v[60:63], v[160:163], v[192:195], v[60:63]
	v_mfma_f32_16x16x32_bf16 v[56:59], v[168:171], v[192:195], v[56:59]
	v_mfma_f32_16x16x32_bf16 v[48:51], v[160:163], v[200:203], v[48:51]
	v_mfma_f32_16x16x32_bf16 v[40:43], v[168:171], v[200:203], v[40:43]
	v_mfma_f32_16x16x32_bf16 v[32:35], v[160:163], v[212:215], v[32:35]
	v_mfma_f32_16x16x32_bf16 v[24:27], v[168:171], v[212:215], v[24:27]
	v_mfma_f32_16x16x32_bf16 v[16:19], v[160:163], v[220:223], v[16:19]
	v_mfma_f32_16x16x32_bf16 v[8:11], v[168:171], v[220:223], v[8:11]
	s_setprio 0
	s_setprio 1
	v_mfma_f32_16x16x32_bf16 v[52:55], v[172:175], v[188:191], 0
	v_mfma_f32_16x16x32_bf16 v[44:47], v[180:183], v[188:191], 0
	v_mfma_f32_16x16x32_bf16 v[36:39], v[172:175], v[196:199], 0
	v_mfma_f32_16x16x32_bf16 v[28:31], v[180:183], v[196:199], 0
	v_mfma_f32_16x16x32_bf16 v[20:23], v[172:175], v[208:211], 0
	v_mfma_f32_16x16x32_bf16 v[12:15], v[180:183], v[208:211], 0
	v_mfma_f32_16x16x32_bf16 v[4:7], v[172:175], v[216:219], 0
	v_mfma_f32_16x16x32_bf16 v[0:3], v[180:183], v[216:219], 0
	v_mfma_f32_16x16x32_bf16 v[52:55], v[176:179], v[192:195], v[52:55]
	v_mfma_f32_16x16x32_bf16 v[44:47], v[184:187], v[192:195], v[44:47]
	v_mfma_f32_16x16x32_bf16 v[36:39], v[176:179], v[200:203], v[36:39]
	v_mfma_f32_16x16x32_bf16 v[28:31], v[184:187], v[200:203], v[28:31]
	v_mfma_f32_16x16x32_bf16 v[20:23], v[176:179], v[212:215], v[20:23]
	v_mfma_f32_16x16x32_bf16 v[12:15], v[184:187], v[212:215], v[12:15]
	v_mfma_f32_16x16x32_bf16 v[4:7], v[176:179], v[220:223], v[4:7]
	v_mfma_f32_16x16x32_bf16 v[0:3], v[184:187], v[220:223], v[0:3]
	s_setprio 0
	s_barrier
	s_add_i32 s19, 0, 0x18000
	v_add_u32_e32 v150, s19, v151
	s_add_i32 s70, 0, 0x1c000
	ds_read_b128 v[156:159], v150
	ds_read_b128 v[160:163], v150 offset:1024
	ds_read_b128 v[164:167], v150 offset:2048
	ds_read_b128 v[168:171], v150 offset:3072
	v_add_u32_e32 v150, s70, v151
	ds_read_b128 v[172:175], v150
	ds_read_b128 v[176:179], v150 offset:1024
	ds_read_b128 v[180:183], v150 offset:2048
	ds_read_b128 v[184:187], v150 offset:3072
	s_add_u32 s62, s62, 0x40000
	s_addc_u32 s63, s63, 0
	s_mov_b32 m0, s57
	v_lshl_add_u64 v[226:227], s[62:63], 0, v[128:129]
	ds_read_b128 v[188:191], v148 offset:32768
	ds_read_b128 v[192:195], v148 offset:33792
	ds_read_b128 v[196:199], v148 offset:34816
	ds_read_b128 v[200:203], v148 offset:35840
	ds_read_b128 v[208:211], v148 offset:36864
	ds_read_b128 v[212:215], v148 offset:37888
	ds_read_b128 v[216:219], v148 offset:38912
	ds_read_b128 v[220:223], v148 offset:39936
	global_load_lds_dwordx4 v[226:227], off
	v_lshl_add_u64 v[226:227], s[62:63], 0, v[132:133]
	s_mov_b32 m0, s64
	s_nop 0
	global_load_lds_dwordx4 v[226:227], off
	s_waitcnt vmcnt(8)
	s_waitcnt lgkmcnt(0)
	s_barrier
	s_setprio 1
	s_waitcnt lgkmcnt(0)
	v_mfma_f32_16x16x32_bf16 v[124:127], v[156:159], v[188:191], v[124:127]
	v_mfma_f32_16x16x32_bf16 v[120:123], v[164:167], v[188:191], v[120:123]
	v_mfma_f32_16x16x32_bf16 v[112:115], v[156:159], v[196:199], v[112:115]
	v_mfma_f32_16x16x32_bf16 v[104:107], v[164:167], v[196:199], v[104:107]
	v_mfma_f32_16x16x32_bf16 v[96:99], v[156:159], v[208:211], v[96:99]
	v_mfma_f32_16x16x32_bf16 v[88:91], v[164:167], v[208:211], v[88:91]
	v_mfma_f32_16x16x32_bf16 v[80:83], v[156:159], v[216:219], v[80:83]
	v_mfma_f32_16x16x32_bf16 v[72:75], v[164:167], v[216:219], v[72:75]
	v_mfma_f32_16x16x32_bf16 v[124:127], v[160:163], v[192:195], v[124:127]
	v_mfma_f32_16x16x32_bf16 v[120:123], v[168:171], v[192:195], v[120:123]
	v_mfma_f32_16x16x32_bf16 v[112:115], v[160:163], v[200:203], v[112:115]
	v_mfma_f32_16x16x32_bf16 v[104:107], v[168:171], v[200:203], v[104:107]
	v_mfma_f32_16x16x32_bf16 v[96:99], v[160:163], v[212:215], v[96:99]
	v_mfma_f32_16x16x32_bf16 v[88:91], v[168:171], v[212:215], v[88:91]
	v_mfma_f32_16x16x32_bf16 v[80:83], v[160:163], v[220:223], v[80:83]
	v_mfma_f32_16x16x32_bf16 v[72:75], v[168:171], v[220:223], v[72:75]
	s_setprio 0
	s_setprio 1
	v_mfma_f32_16x16x32_bf16 v[116:119], v[172:175], v[188:191], v[116:119]
	v_mfma_f32_16x16x32_bf16 v[108:111], v[180:183], v[188:191], v[108:111]
	v_mfma_f32_16x16x32_bf16 v[100:103], v[172:175], v[196:199], v[100:103]
	v_mfma_f32_16x16x32_bf16 v[92:95], v[180:183], v[196:199], v[92:95]
	v_mfma_f32_16x16x32_bf16 v[84:87], v[172:175], v[208:211], v[84:87]
	v_mfma_f32_16x16x32_bf16 v[76:79], v[180:183], v[208:211], v[76:79]
	v_mfma_f32_16x16x32_bf16 v[68:71], v[172:175], v[216:219], v[68:71]
	v_mfma_f32_16x16x32_bf16 v[64:67], v[180:183], v[216:219], v[64:67]
	v_mfma_f32_16x16x32_bf16 v[116:119], v[176:179], v[192:195], v[116:119]
	v_mfma_f32_16x16x32_bf16 v[108:111], v[184:187], v[192:195], v[108:111]
	v_mfma_f32_16x16x32_bf16 v[100:103], v[176:179], v[200:203], v[100:103]
	v_mfma_f32_16x16x32_bf16 v[92:95], v[184:187], v[200:203], v[92:95]
	v_mfma_f32_16x16x32_bf16 v[84:87], v[176:179], v[212:215], v[84:87]
	v_mfma_f32_16x16x32_bf16 v[76:79], v[184:187], v[212:215], v[76:79]
	v_mfma_f32_16x16x32_bf16 v[68:71], v[176:179], v[220:223], v[68:71]
	v_mfma_f32_16x16x32_bf16 v[64:67], v[184:187], v[220:223], v[64:67]
	s_setprio 0
	s_barrier
; #define PG8_STAGE(bufoff, gbase, voff) do { _Pragma("unroll") for (int _i = 0; _i < 2; ++_i) \
;         __builtin_amdgcn_global_load_lds((const unsigned*)((const char*)(gbase) + (voff)[_i]), (PG8_LAS unsigned*)(lds + (bufoff) + ldsw + _i * 8192), 16, 0, 0); } while (0)
; #define PG8_LDA(dst, b, h) do { _Pragma("unroll") for (int m = 0; m < 4; ++m) _Pragma("unroll") for (int k = 0; k < 2; ++k) dst[m][k] = *(const PG8_LAS bf16x8*)(lds + PG8_SA(b, h) + aoff + m * 2048 + k * 1024); } while (0)
; #define PG8_MMA(ai, bj, At, Bt) do { __builtin_amdgcn_s_setprio(1); _Pragma("unroll") for (int m = 0; m < 4; ++m) _Pragma("unroll") for (int n = 0; n < 2; ++n) _Pragma("unroll") for (int k = 0; k < 2; ++k) \
;         acc[ai][bj][m][n] = __builtin_amdgcn_mfma_f32_16x16x32_bf16(Bt[n][k], At[m][k], acc[ai][bj][m][n], 0, 0, 0); __builtin_amdgcn_s_setprio(0); } while (0)
; #define PG8_WAIT_V(n) asm volatile("s_waitcnt vmcnt(" #n ")" ::: "memory")
; #define PG8_WAIT_L(n) asm volatile("s_waitcnt lgkmcnt(" #n ")" ::: "memory")
; #define PG8_BAR __builtin_amdgcn_s_barrier()
; #define PG8_SCHED __builtin_amdgcn_sched_barrier(0)
; template <class Epi, class Sched, bool ALIGN_EPI = false, bool SP2 = false>
; __device__ __forceinline__ void gemm_phase(PG8_LAS unsigned char* lds, const Gemm g, const Sched& S, const Epi& E) {
;     ...
;         for (int t = 0; t < nt; t += 2) {
;             const bool last = (t == nt - 2);
;     ...
;             PG8_LDA(At, 1, 1); PG8_STAGE(PG8_SB(1, 0), b3, voffB); PG8_STAGE(PG8_SB(1, 1), b3 + hstep, voffB); PG8_STAGE(PG8_SA(1, 0), a3, voffA);
;             PG8_WAIT_V(8); PG8_WAIT_L(0); PG8_BAR; PG8_MMA(1, 0, At, B0); PG8_MMA(1, 1, At, B1); PG8_BAR; PG8_SCHED;
	s_add_i32 s19, s19, s23
	v_lshl_add_u64 v[144:145], v[144:145], 0, s[8:9]
	s_mov_b32 m0, s19
	ds_read_b128 v[188:191], v148 offset:49152
	ds_read_b128 v[192:195], v148 offset:50176
	ds_read_b128 v[196:199], v148 offset:51200
	ds_read_b128 v[200:203], v148 offset:52224
	ds_read_b128 v[208:211], v148 offset:53248
	ds_read_b128 v[212:215], v148 offset:54272
	ds_read_b128 v[216:219], v148 offset:55296
	ds_read_b128 v[220:223], v148 offset:56320
	global_load_lds_dwordx4 v[144:145], off
	s_add_i32 m0, s19, 0x2000
	s_add_u32 s60, s60, 0x40080
	v_lshl_add_u64 v[144:145], v[152:153], 0, s[8:9]
	s_addc_u32 s61, s61, 0
	s_add_i32 s19, s70, s23
	global_load_lds_dwordx4 v[144:145], off
	v_lshl_add_u64 v[144:145], s[60:61], 0, v[130:131]
	s_mov_b32 m0, s19
	s_nop 0
	global_load_lds_dwordx4 v[144:145], off
	v_lshl_add_u64 v[144:145], s[60:61], 0, v[134:135]
	s_add_i32 m0, s19, 0x2000
	s_nop 0
	global_load_lds_dwordx4 v[144:145], off
	v_lshl_add_u64 v[144:145], v[204:205], 0, s[8:9]
	s_mov_b32 m0, s66
	s_nop 0
	global_load_lds_dwordx4 v[144:145], off
	v_lshl_add_u64 v[144:145], v[224:225], 0, s[8:9]
	s_mov_b32 m0, s67
	s_nop 0
	global_load_lds_dwordx4 v[144:145], off
	s_waitcnt vmcnt(8)
	s_waitcnt lgkmcnt(0)
	s_barrier
	s_setprio 1
	s_waitcnt lgkmcnt(0)
	v_mfma_f32_16x16x32_bf16 v[60:63], v[156:159], v[188:191], v[60:63]
	v_mfma_f32_16x16x32_bf16 v[56:59], v[164:167], v[188:191], v[56:59]
	v_mfma_f32_16x16x32_bf16 v[48:51], v[156:159], v[196:199], v[48:51]
	v_mfma_f32_16x16x32_bf16 v[40:43], v[164:167], v[196:199], v[40:43]
	v_mfma_f32_16x16x32_bf16 v[32:35], v[156:159], v[208:211], v[32:35]
	v_mfma_f32_16x16x32_bf16 v[24:27], v[164:167], v[208:211], v[24:27]
	v_mfma_f32_16x16x32_bf16 v[16:19], v[156:159], v[216:219], v[16:19]
	v_mfma_f32_16x16x32_bf16 v[8:11], v[164:167], v[216:219], v[8:11]
	v_mfma_f32_16x16x32_bf16 v[60:63], v[160:163], v[192:195], v[60:63]
	v_mfma_f32_16x16x32_bf16 v[56:59], v[168:171], v[192:195], v[56:59]
	v_mfma_f32_16x16x32_bf16 v[48:51], v[160:163], v[200:203], v[48:51]
	v_mfma_f32_16x16x32_bf16 v[40:43], v[168:171], v[200:203], v[40:43]
	v_mfma_f32_16x16x32_bf16 v[32:35], v[160:163], v[212:215], v[32:35]
	v_mfma_f32_16x16x32_bf16 v[24:27], v[168:171], v[212:215], v[24:27]
	v_mfma_f32_16x16x32_bf16 v[16:19], v[160:163], v[220:223], v[16:19]
	v_mfma_f32_16x16x32_bf16 v[8:11], v[168:171], v[220:223], v[8:11]
	s_setprio 0
	s_setprio 1
	v_mfma_f32_16x16x32_bf16 v[52:55], v[172:175], v[188:191], v[52:55]
	v_mfma_f32_16x16x32_bf16 v[44:47], v[180:183], v[188:191], v[44:47]
	v_mfma_f32_16x16x32_bf16 v[36:39], v[172:175], v[196:199], v[36:39]
	v_mfma_f32_16x16x32_bf16 v[28:31], v[180:183], v[196:199], v[28:31]
	v_mfma_f32_16x16x32_bf16 v[20:23], v[172:175], v[208:211], v[20:23]
	v_mfma_f32_16x16x32_bf16 v[12:15], v[180:183], v[208:211], v[12:15]
	v_mfma_f32_16x16x32_bf16 v[4:7], v[172:175], v[216:219], v[4:7]
	v_mfma_f32_16x16x32_bf16 v[0:3], v[180:183], v[216:219], v[0:3]
	v_mfma_f32_16x16x32_bf16 v[52:55], v[176:179], v[192:195], v[52:55]
	v_mfma_f32_16x16x32_bf16 v[44:47], v[184:187], v[192:195], v[44:47]
	v_mfma_f32_16x16x32_bf16 v[36:39], v[176:179], v[200:203], v[36:39]
	v_mfma_f32_16x16x32_bf16 v[28:31], v[184:187], v[200:203], v[28:31]
	v_mfma_f32_16x16x32_bf16 v[20:23], v[176:179], v[212:215], v[20:23]
	v_mfma_f32_16x16x32_bf16 v[12:15], v[184:187], v[212:215], v[12:15]
	v_mfma_f32_16x16x32_bf16 v[4:7], v[176:179], v[220:223], v[4:7]
	v_mfma_f32_16x16x32_bf16 v[0:3], v[184:187], v[220:223], v[0:3]
	s_setprio 0
	s_barrier
	s_add_i32 s93, s93, 2
	s_add_u32 s58, s58, 0x100
	s_addc_u32 s59, s59, 0
	s_add_u32 s91, s91, 0x100
	s_addc_u32 s92, s92, 0
	s_cmp_gt_u32 s93, 13
	s_cbranch_scc1 .Lpeel_exit_1

; #define PG8_STAGE(bufoff, gbase, voff) do { _Pragma("unroll") for (int _i = 0; _i < 2; ++_i) \
;         __builtin_amdgcn_global_load_lds((const unsigned*)((const char*)(gbase) + (voff)[_i]), (PG8_LAS unsigned*)(lds + (bufoff) + ldsw + _i * 8192), 16, 0, 0); } while (0)
; #define PG8_LDA(dst, b, h) do { _Pragma("unroll") for (int m = 0; m < 4; ++m) _Pragma("unroll") for (int k = 0; k < 2; ++k) dst[m][k] = *(const PG8_LAS bf16x8*)(lds + PG8_SA(b, h) + aoff + m * 2048 + k * 1024); } while (0)
; #define PG8_LDB(dst, b, h) do { _Pragma("unroll") for (int n = 0; n < 2; ++n) _Pragma("unroll") for (int k = 0; k < 2; ++k) dst[n][k] = *(const PG8_LAS bf16x8*)(lds + PG8_SB(b, h) + boff + n * 2048 + k * 1024); } while (0)
; template <class Epi, class Sched, bool ALIGN_EPI = false, bool SP2 = false>
; __device__ __forceinline__ void gemm_phase(PG8_LAS unsigned char* lds, const Gemm g, const Sched& S, const Epi& E) {
;     ...
;     f32x4 acc[2][2][4][2];
; #pragma unroll
;     for (int a = 0; a < 2; ++a)
; #pragma unroll
;         for (int b = 0; b < 2; ++b)
; #pragma unroll
;             for (int m = 0; m < 4; ++m)
; #pragma unroll
;                 for (int n = 0; n < 2; ++n) acc[a][b][m][n] = (f32x4){0.f, 0.f, 0.f, 0.f};
;     ...
;         const bool has_next = S.next(ui + 1, nxt);
;         const char* nA = has_next ? (const char*)g.A + (size_t)nxt.pm * tstep : cA; const char* nB = has_next ? (const char*)g.Bt + (size_t)nxt.pn * tstep : cB;
;         for (int t = 0; t < nt; t += 2) {
;             const bool last = (t == nt - 2);
;             const char* a1 = cA + (size_t)(t + 1) * kstep;
;             const char* a2 = last ? nA : cA + (size_t)(t + 2) * kstep; const char* b2 = last ? nB : cB + (size_t)(t + 2) * kstep;
;             const char* a3 = a2 + kstep; const char* b3 = b2 + kstep;
;             if (last && has_next) S.a_ready(nxt);
;             if constexpr (SP2) {
;             PG8_LDB(B0, 0, 0); PG8_LDB(B1, 0, 1); PG8_SCHED; PG8_LDA(At, 0, 0); PG8_STAGE(PG8_SA(1, 1), a1 + hstep, voffA);
;             PG8_WAIT_V(8); PG8_WAIT_L(0); PG8_BAR; PG8_MMA(0, 0, At, B0); PG8_MMA(0, 1, At, B1); PG8_BAR; PG8_SCHED;
;             PG8_LDA(At, 0, 1); PG8_STAGE(PG8_SB(0, 0), b2, voffB); PG8_STAGE(PG8_SB(0, 1), b2 + hstep, voffB); PG8_STAGE(PG8_SA(0, 0), a2, voffA);
;             PG8_WAIT_V(8); PG8_WAIT_L(0); PG8_BAR; PG8_MMA(1, 0, At, B0); PG8_MMA(1, 1, At, B1); PG8_BAR; PG8_SCHED;
.LBB0_479:
	s_ashr_i32 s45, s44, 31
	s_lshl_b64 s[46:47], s[44:45], 19
	s_add_u32 s46, s40, s46
	s_addc_u32 s47, s41, s47
	s_and_b64 s[48:49], s[4:5], exec
	s_cselect_b32 s45, s47, s55
	s_cselect_b32 s51, s46, s54
	s_ashr_i32 s43, s42, 31
	s_lshl_b64 s[48:49], s[42:43], 19
	s_add_u32 s48, s72, s48
	s_addc_u32 s49, s73, s49
	s_and_b64 s[58:59], s[4:5], exec
	s_cselect_b32 s43, s49, s57
	s_cselect_b32 s67, s48, s56
	s_add_u32 s54, s54, 0x40080
	s_addc_u32 s55, s55, 0
	s_add_u32 s74, s56, 0x100
	s_addc_u32 s75, s57, 0
	s_mov_b32 s76, -2
	s_waitcnt lgkmcnt(0)
	ds_read_b128 v[128:131], v167
	ds_read_b128 v[132:135], v167 offset:1024
	ds_read_b128 v[160:163], v167 offset:2048
	ds_read_b128 v[172:175], v167 offset:3072
	ds_read_b128 v[178:181], v171
	ds_read_b128 v[184:187], v171 offset:1024
	ds_read_b128 v[188:191], v171 offset:2048
	ds_read_b128 v[192:195], v171 offset:3072
	s_add_u32 s19, s54, 0xfffc0080
	s_addc_u32 s56, s55, -1
	s_cmp_eq_u32 s76, 12
	s_cselect_b32 s59, s45, s56
	s_cselect_b32 s58, s51, s19
	s_cselect_b32 s57, s43, s75
	s_cselect_b32 s56, s67, s74
	v_lshl_add_u64 v[152:153], s[54:55], 0, v[144:145]
	s_add_i32 m0, s15, 0xc000
	ds_read_b128 v[196:199], v177
	ds_read_b128 v[200:203], v177 offset:1024
	ds_read_b128 v[208:211], v177 offset:2048
	ds_read_b128 v[212:215], v177 offset:3072
	ds_read_b128 v[216:219], v177 offset:4096
	ds_read_b128 v[220:223], v177 offset:5120
	ds_read_b128 v[224:227], v177 offset:6144
	ds_read_b128 v[228:231], v177 offset:7168
	global_load_lds_dwordx4 v[152:153], off
	v_lshl_add_u64 v[152:153], s[54:55], 0, v[146:147]
	s_add_i32 m0, s15, 0xe000
	s_nop 0
	global_load_lds_dwordx4 v[152:153], off
	s_waitcnt vmcnt(8)
	s_waitcnt lgkmcnt(0)
	s_barrier
	s_setprio 1
	s_waitcnt lgkmcnt(0)
	v_mfma_f32_16x16x32_bf16 v[124:127], v[128:131], v[196:199], 0
	v_mfma_f32_16x16x32_bf16 v[120:123], v[160:163], v[196:199], 0
	v_mfma_f32_16x16x32_bf16 v[108:111], v[128:131], v[208:211], 0
	v_mfma_f32_16x16x32_bf16 v[104:107], v[160:163], v[208:211], 0
	v_mfma_f32_16x16x32_bf16 v[92:95], v[128:131], v[216:219], 0
	v_mfma_f32_16x16x32_bf16 v[88:91], v[160:163], v[216:219], 0
	v_mfma_f32_16x16x32_bf16 v[76:79], v[128:131], v[224:227], 0
	v_mfma_f32_16x16x32_bf16 v[72:75], v[160:163], v[224:227], 0
	v_mfma_f32_16x16x32_bf16 v[124:127], v[132:135], v[200:203], v[124:127]
	v_mfma_f32_16x16x32_bf16 v[120:123], v[172:175], v[200:203], v[120:123]
	v_mfma_f32_16x16x32_bf16 v[108:111], v[132:135], v[212:215], v[108:111]
	v_mfma_f32_16x16x32_bf16 v[104:107], v[172:175], v[212:215], v[104:107]
	v_mfma_f32_16x16x32_bf16 v[92:95], v[132:135], v[220:223], v[92:95]
	v_mfma_f32_16x16x32_bf16 v[88:91], v[172:175], v[220:223], v[88:91]
	v_mfma_f32_16x16x32_bf16 v[76:79], v[132:135], v[228:231], v[76:79]
	v_mfma_f32_16x16x32_bf16 v[72:75], v[172:175], v[228:231], v[72:75]
	s_setprio 0
	s_setprio 1
	v_mfma_f32_16x16x32_bf16 v[116:119], v[178:181], v[196:199], 0
	v_mfma_f32_16x16x32_bf16 v[112:115], v[188:191], v[196:199], 0
	v_mfma_f32_16x16x32_bf16 v[100:103], v[178:181], v[208:211], 0
	v_mfma_f32_16x16x32_bf16 v[96:99], v[188:191], v[208:211], 0
	v_mfma_f32_16x16x32_bf16 v[84:87], v[178:181], v[216:219], 0
	v_mfma_f32_16x16x32_bf16 v[80:83], v[188:191], v[216:219], 0
	v_mfma_f32_16x16x32_bf16 v[68:71], v[178:181], v[224:227], 0
	v_mfma_f32_16x16x32_bf16 v[64:67], v[188:191], v[224:227], 0
	v_mfma_f32_16x16x32_bf16 v[116:119], v[184:187], v[200:203], v[116:119]
	v_mfma_f32_16x16x32_bf16 v[112:115], v[192:195], v[200:203], v[112:115]
	v_mfma_f32_16x16x32_bf16 v[100:103], v[184:187], v[212:215], v[100:103]
	v_mfma_f32_16x16x32_bf16 v[96:99], v[192:195], v[212:215], v[96:99]
	v_mfma_f32_16x16x32_bf16 v[84:87], v[184:187], v[220:223], v[84:87]
	v_mfma_f32_16x16x32_bf16 v[80:83], v[192:195], v[220:223], v[80:83]
	v_mfma_f32_16x16x32_bf16 v[68:71], v[184:187], v[228:231], v[68:71]
	v_mfma_f32_16x16x32_bf16 v[64:67], v[192:195], v[228:231], v[64:67]
	s_setprio 0
	s_barrier
	s_add_i32 s19, s64, s14
	v_lshl_add_u64 v[152:153], s[56:57], 0, v[138:139]
	s_mov_b32 m0, s19
	ds_read_b128 v[196:199], v177 offset:16384
	ds_read_b128 v[200:203], v177 offset:17408
	ds_read_b128 v[208:211], v177 offset:18432
	ds_read_b128 v[212:215], v177 offset:19456
	ds_read_b128 v[216:219], v177 offset:20480
	ds_read_b128 v[220:223], v177 offset:21504
	ds_read_b128 v[224:227], v177 offset:22528
	ds_read_b128 v[228:231], v177 offset:23552
	global_load_lds_dwordx4 v[152:153], off
	s_add_i32 m0, s19, 0x2000
	s_add_u32 s70, s56, 0x40000
	v_lshl_add_u64 v[156:157], s[56:57], 0, v[142:143]
	s_addc_u32 s71, s57, 0
	s_add_i32 s19, s65, s14
	global_load_lds_dwordx4 v[156:157], off
	v_lshl_add_u64 v[168:169], s[70:71], 0, v[138:139]
	s_mov_b32 m0, s19
	v_lshl_add_u64 v[204:205], s[58:59], 0, v[140:141]
	global_load_lds_dwordx4 v[168:169], off
	v_lshl_add_u64 v[168:169], s[70:71], 0, v[142:143]
	s_add_i32 m0, s19, 0x2000
	s_nop 0
	global_load_lds_dwordx4 v[168:169], off
	v_lshl_add_u64 v[168:169], s[58:59], 0, v[136:137]
	s_mov_b32 m0, s15
	s_nop 0
	global_load_lds_dwordx4 v[168:169], off
	s_mov_b32 m0, s18
	s_nop 0
	global_load_lds_dwordx4 v[204:205], off
	s_waitcnt vmcnt(8)
	s_waitcnt lgkmcnt(0)
	s_barrier
; #define PG8_STAGE(bufoff, gbase, voff) do { _Pragma("unroll") for (int _i = 0; _i < 2; ++_i) \
;         __builtin_amdgcn_global_load_lds((const unsigned*)((const char*)(gbase) + (voff)[_i]), (PG8_LAS unsigned*)(lds + (bufoff) + ldsw + _i * 8192), 16, 0, 0); } while (0)
; #define PG8_LDA(dst, b, h) do { _Pragma("unroll") for (int m = 0; m < 4; ++m) _Pragma("unroll") for (int k = 0; k < 2; ++k) dst[m][k] = *(const PG8_LAS bf16x8*)(lds + PG8_SA(b, h) + aoff + m * 2048 + k * 1024); } while (0)
; #define PG8_LDB(dst, b, h) do { _Pragma("unroll") for (int n = 0; n < 2; ++n) _Pragma("unroll") for (int k = 0; k < 2; ++k) dst[n][k] = *(const PG8_LAS bf16x8*)(lds + PG8_SB(b, h) + boff + n * 2048 + k * 1024); } while (0)
; #define PG8_MMA(ai, bj, At, Bt) do { __builtin_amdgcn_s_setprio(1); _Pragma("unroll") for (int m = 0; m < 4; ++m) _Pragma("unroll") for (int n = 0; n < 2; ++n) _Pragma("unroll") for (int k = 0; k < 2; ++k) \
;         acc[ai][bj][m][n] = __builtin_amdgcn_mfma_f32_16x16x32_bf16(Bt[n][k], At[m][k], acc[ai][bj][m][n], 0, 0, 0); __builtin_amdgcn_s_setprio(0); } while (0)
; #define PG8_WAIT_V(n) asm volatile("s_waitcnt vmcnt(" #n ")" ::: "memory")
; #define PG8_WAIT_L(n) asm volatile("s_waitcnt lgkmcnt(" #n ")" ::: "memory")
; #define PG8_BAR __builtin_amdgcn_s_barrier()
; #define PG8_SCHED __builtin_amdgcn_sched_barrier(0)
; template <class Epi, class Sched, bool ALIGN_EPI = false, bool SP2 = false>
; __device__ __forceinline__ void gemm_phase(PG8_LAS unsigned char* lds, const Gemm g, const Sched& S, const Epi& E) {
;     ...
;             PG8_WAIT_V(8); PG8_WAIT_L(0); PG8_BAR; PG8_MMA(1, 0, At, B0); PG8_MMA(1, 1, At, B1); PG8_BAR; PG8_SCHED;
;             PG8_LDB(B0, 1, 0); PG8_LDB(B1, 1, 1); PG8_SCHED; PG8_LDA(At, 1, 0); PG8_STAGE(PG8_SA(0, 1), a2 + hstep, voffA);
;             PG8_WAIT_V(8); PG8_WAIT_L(0); PG8_BAR; PG8_MMA(0, 0, At, B0); PG8_MMA(0, 1, At, B1); PG8_BAR; PG8_SCHED;
	s_setprio 1
	s_waitcnt lgkmcnt(0)
	v_mfma_f32_16x16x32_bf16 v[60:63], v[128:131], v[196:199], 0
	v_mfma_f32_16x16x32_bf16 v[56:59], v[160:163], v[196:199], 0
	v_mfma_f32_16x16x32_bf16 v[44:47], v[128:131], v[208:211], 0
	v_mfma_f32_16x16x32_bf16 v[40:43], v[160:163], v[208:211], 0
	v_mfma_f32_16x16x32_bf16 v[28:31], v[128:131], v[216:219], 0
	v_mfma_f32_16x16x32_bf16 v[24:27], v[160:163], v[216:219], 0
	v_mfma_f32_16x16x32_bf16 v[12:15], v[128:131], v[224:227], 0
	v_mfma_f32_16x16x32_bf16 v[8:11], v[160:163], v[224:227], 0
	v_mfma_f32_16x16x32_bf16 v[60:63], v[132:135], v[200:203], v[60:63]
	v_mfma_f32_16x16x32_bf16 v[56:59], v[172:175], v[200:203], v[56:59]
	v_mfma_f32_16x16x32_bf16 v[44:47], v[132:135], v[212:215], v[44:47]
	v_mfma_f32_16x16x32_bf16 v[40:43], v[172:175], v[212:215], v[40:43]
	v_mfma_f32_16x16x32_bf16 v[28:31], v[132:135], v[220:223], v[28:31]
	v_mfma_f32_16x16x32_bf16 v[24:27], v[172:175], v[220:223], v[24:27]
	v_mfma_f32_16x16x32_bf16 v[12:15], v[132:135], v[228:231], v[12:15]
	v_mfma_f32_16x16x32_bf16 v[8:11], v[172:175], v[228:231], v[8:11]
	s_setprio 0
	s_setprio 1
	v_mfma_f32_16x16x32_bf16 v[52:55], v[178:181], v[196:199], 0
	v_mfma_f32_16x16x32_bf16 v[48:51], v[188:191], v[196:199], 0
	v_mfma_f32_16x16x32_bf16 v[36:39], v[178:181], v[208:211], 0
	v_mfma_f32_16x16x32_bf16 v[32:35], v[188:191], v[208:211], 0
	v_mfma_f32_16x16x32_bf16 v[20:23], v[178:181], v[216:219], 0
	v_mfma_f32_16x16x32_bf16 v[16:19], v[188:191], v[216:219], 0
	v_mfma_f32_16x16x32_bf16 v[4:7], v[178:181], v[224:227], 0
	v_mfma_f32_16x16x32_bf16 v[0:3], v[188:191], v[224:227], 0
	v_mfma_f32_16x16x32_bf16 v[52:55], v[184:187], v[200:203], v[52:55]
	v_mfma_f32_16x16x32_bf16 v[48:51], v[192:195], v[200:203], v[48:51]
	v_mfma_f32_16x16x32_bf16 v[36:39], v[184:187], v[212:215], v[36:39]
	v_mfma_f32_16x16x32_bf16 v[32:35], v[192:195], v[212:215], v[32:35]
	v_mfma_f32_16x16x32_bf16 v[20:23], v[184:187], v[220:223], v[20:23]
	v_mfma_f32_16x16x32_bf16 v[16:19], v[192:195], v[220:223], v[16:19]
	v_mfma_f32_16x16x32_bf16 v[4:7], v[184:187], v[228:231], v[4:7]
	v_mfma_f32_16x16x32_bf16 v[0:3], v[192:195], v[228:231], v[0:3]
	s_setprio 0
	s_barrier
	s_add_i32 s19, 0, 0x18000
	v_add_u32_e32 v154, s19, v159
	s_add_i32 s70, 0, 0x1c000
	ds_read_b128 v[128:131], v154
	ds_read_b128 v[132:135], v154 offset:1024
	ds_read_b128 v[160:163], v154 offset:2048
	ds_read_b128 v[172:175], v154 offset:3072
	v_add_u32_e32 v154, s70, v159
	ds_read_b128 v[178:181], v154
	ds_read_b128 v[184:187], v154 offset:1024
	ds_read_b128 v[188:191], v154 offset:2048
	ds_read_b128 v[192:195], v154 offset:3072
	s_add_u32 s58, s58, 0x40000
	s_addc_u32 s59, s59, 0
	s_mov_b32 m0, s23
	v_lshl_add_u64 v[232:233], s[58:59], 0, v[136:137]
	ds_read_b128 v[196:199], v177 offset:32768
	ds_read_b128 v[200:203], v177 offset:33792
	ds_read_b128 v[208:211], v177 offset:34816
	ds_read_b128 v[212:215], v177 offset:35840
	ds_read_b128 v[216:219], v177 offset:36864
	ds_read_b128 v[220:223], v177 offset:37888
	ds_read_b128 v[224:227], v177 offset:38912
	ds_read_b128 v[228:231], v177 offset:39936
	global_load_lds_dwordx4 v[232:233], off
	v_lshl_add_u64 v[232:233], s[58:59], 0, v[140:141]
	s_mov_b32 m0, s33
	s_nop 0
	global_load_lds_dwordx4 v[232:233], off
	s_waitcnt vmcnt(8)
	s_waitcnt lgkmcnt(0)
	s_barrier
	s_setprio 1
	s_waitcnt lgkmcnt(0)
	v_mfma_f32_16x16x32_bf16 v[124:127], v[128:131], v[196:199], v[124:127]
	v_mfma_f32_16x16x32_bf16 v[120:123], v[160:163], v[196:199], v[120:123]
	v_mfma_f32_16x16x32_bf16 v[108:111], v[128:131], v[208:211], v[108:111]
	v_mfma_f32_16x16x32_bf16 v[104:107], v[160:163], v[208:211], v[104:107]
	v_mfma_f32_16x16x32_bf16 v[92:95], v[128:131], v[216:219], v[92:95]
	v_mfma_f32_16x16x32_bf16 v[88:91], v[160:163], v[216:219], v[88:91]
	v_mfma_f32_16x16x32_bf16 v[76:79], v[128:131], v[224:227], v[76:79]
	v_mfma_f32_16x16x32_bf16 v[72:75], v[160:163], v[224:227], v[72:75]
	v_mfma_f32_16x16x32_bf16 v[124:127], v[132:135], v[200:203], v[124:127]
	v_mfma_f32_16x16x32_bf16 v[120:123], v[172:175], v[200:203], v[120:123]
	v_mfma_f32_16x16x32_bf16 v[108:111], v[132:135], v[212:215], v[108:111]
	v_mfma_f32_16x16x32_bf16 v[104:107], v[172:175], v[212:215], v[104:107]
	v_mfma_f32_16x16x32_bf16 v[92:95], v[132:135], v[220:223], v[92:95]
	v_mfma_f32_16x16x32_bf16 v[88:91], v[172:175], v[220:223], v[88:91]
	v_mfma_f32_16x16x32_bf16 v[76:79], v[132:135], v[228:231], v[76:79]
	v_mfma_f32_16x16x32_bf16 v[72:75], v[172:175], v[228:231], v[72:75]
	s_setprio 0
	s_setprio 1
	v_mfma_f32_16x16x32_bf16 v[116:119], v[178:181], v[196:199], v[116:119]
	v_mfma_f32_16x16x32_bf16 v[112:115], v[188:191], v[196:199], v[112:115]
	v_mfma_f32_16x16x32_bf16 v[100:103], v[178:181], v[208:211], v[100:103]
	v_mfma_f32_16x16x32_bf16 v[96:99], v[188:191], v[208:211], v[96:99]
	v_mfma_f32_16x16x32_bf16 v[84:87], v[178:181], v[216:219], v[84:87]
	v_mfma_f32_16x16x32_bf16 v[80:83], v[188:191], v[216:219], v[80:83]
	v_mfma_f32_16x16x32_bf16 v[68:71], v[178:181], v[224:227], v[68:71]
	v_mfma_f32_16x16x32_bf16 v[64:67], v[188:191], v[224:227], v[64:67]
	v_mfma_f32_16x16x32_bf16 v[116:119], v[184:187], v[200:203], v[116:119]
	v_mfma_f32_16x16x32_bf16 v[112:115], v[192:195], v[200:203], v[112:115]
	v_mfma_f32_16x16x32_bf16 v[100:103], v[184:187], v[212:215], v[100:103]
	v_mfma_f32_16x16x32_bf16 v[96:99], v[192:195], v[212:215], v[96:99]
	v_mfma_f32_16x16x32_bf16 v[84:87], v[184:187], v[220:223], v[84:87]
	v_mfma_f32_16x16x32_bf16 v[80:83], v[192:195], v[220:223], v[80:83]
	v_mfma_f32_16x16x32_bf16 v[68:71], v[184:187], v[228:231], v[68:71]
	v_mfma_f32_16x16x32_bf16 v[64:67], v[192:195], v[228:231], v[64:67]
	s_setprio 0
	s_barrier
; #define PG8_STAGE(bufoff, gbase, voff) do { _Pragma("unroll") for (int _i = 0; _i < 2; ++_i) \
;         __builtin_amdgcn_global_load_lds((const unsigned*)((const char*)(gbase) + (voff)[_i]), (PG8_LAS unsigned*)(lds + (bufoff) + ldsw + _i * 8192), 16, 0, 0); } while (0)
; #define PG8_LDA(dst, b, h) do { _Pragma("unroll") for (int m = 0; m < 4; ++m) _Pragma("unroll") for (int k = 0; k < 2; ++k) dst[m][k] = *(const PG8_LAS bf16x8*)(lds + PG8_SA(b, h) + aoff + m * 2048 + k * 1024); } while (0)
; #define PG8_MMA(ai, bj, At, Bt) do { __builtin_amdgcn_s_setprio(1); _Pragma("unroll") for (int m = 0; m < 4; ++m) _Pragma("unroll") for (int n = 0; n < 2; ++n) _Pragma("unroll") for (int k = 0; k < 2; ++k) \
;         acc[ai][bj][m][n] = __builtin_amdgcn_mfma_f32_16x16x32_bf16(Bt[n][k], At[m][k], acc[ai][bj][m][n], 0, 0, 0); __builtin_amdgcn_s_setprio(0); } while (0)
; #define PG8_WAIT_V(n) asm volatile("s_waitcnt vmcnt(" #n ")" ::: "memory")
; #define PG8_WAIT_L(n) asm volatile("s_waitcnt lgkmcnt(" #n ")" ::: "memory")
; #define PG8_BAR __builtin_amdgcn_s_barrier()
; #define PG8_SCHED __builtin_amdgcn_sched_barrier(0)
; template <class Epi, class Sched, bool ALIGN_EPI = false, bool SP2 = false>
; __device__ __forceinline__ void gemm_phase(PG8_LAS unsigned char* lds, const Gemm g, const Sched& S, const Epi& E) {
;     ...
;         for (int t = 0; t < nt; t += 2) {
;             const bool last = (t == nt - 2);
;     ...
;             PG8_LDA(At, 1, 1); PG8_STAGE(PG8_SB(1, 0), b3, voffB); PG8_STAGE(PG8_SB(1, 1), b3 + hstep, voffB); PG8_STAGE(PG8_SA(1, 0), a3, voffA);
;             PG8_WAIT_V(8); PG8_WAIT_L(0); PG8_BAR; PG8_MMA(1, 0, At, B0); PG8_MMA(1, 1, At, B1); PG8_BAR; PG8_SCHED;
	s_add_i32 s19, s19, s14
	v_lshl_add_u64 v[152:153], v[152:153], 0, s[12:13]
	s_mov_b32 m0, s19
	ds_read_b128 v[196:199], v177 offset:49152
	ds_read_b128 v[200:203], v177 offset:50176
	ds_read_b128 v[208:211], v177 offset:51200
	ds_read_b128 v[212:215], v177 offset:52224
	ds_read_b128 v[216:219], v177 offset:53248
	ds_read_b128 v[220:223], v177 offset:54272
	ds_read_b128 v[224:227], v177 offset:55296
	ds_read_b128 v[228:231], v177 offset:56320
	global_load_lds_dwordx4 v[152:153], off
	s_add_i32 m0, s19, 0x2000
	s_add_u32 s56, s56, 0x40080
	v_lshl_add_u64 v[152:153], v[156:157], 0, s[12:13]
	s_addc_u32 s57, s57, 0
	s_add_i32 s19, s70, s14
	global_load_lds_dwordx4 v[152:153], off
	v_lshl_add_u64 v[152:153], s[56:57], 0, v[138:139]
	s_mov_b32 m0, s19
	s_nop 0
	global_load_lds_dwordx4 v[152:153], off
	v_lshl_add_u64 v[152:153], s[56:57], 0, v[142:143]
	s_add_i32 m0, s19, 0x2000
	s_nop 0
	global_load_lds_dwordx4 v[152:153], off
	v_lshl_add_u64 v[152:153], v[168:169], 0, s[12:13]
	s_mov_b32 m0, s53
	s_nop 0
	global_load_lds_dwordx4 v[152:153], off
	v_lshl_add_u64 v[152:153], v[204:205], 0, s[12:13]
	s_mov_b32 m0, s60
	s_nop 0
	global_load_lds_dwordx4 v[152:153], off
	s_waitcnt vmcnt(8)
	s_waitcnt lgkmcnt(0)
	s_barrier
	s_setprio 1
	s_waitcnt lgkmcnt(0)
	v_mfma_f32_16x16x32_bf16 v[60:63], v[128:131], v[196:199], v[60:63]
	v_mfma_f32_16x16x32_bf16 v[56:59], v[160:163], v[196:199], v[56:59]
	v_mfma_f32_16x16x32_bf16 v[44:47], v[128:131], v[208:211], v[44:47]
	v_mfma_f32_16x16x32_bf16 v[40:43], v[160:163], v[208:211], v[40:43]
	v_mfma_f32_16x16x32_bf16 v[28:31], v[128:131], v[216:219], v[28:31]
	v_mfma_f32_16x16x32_bf16 v[24:27], v[160:163], v[216:219], v[24:27]
	v_mfma_f32_16x16x32_bf16 v[12:15], v[128:131], v[224:227], v[12:15]
	v_mfma_f32_16x16x32_bf16 v[8:11], v[160:163], v[224:227], v[8:11]
	v_mfma_f32_16x16x32_bf16 v[60:63], v[132:135], v[200:203], v[60:63]
	v_mfma_f32_16x16x32_bf16 v[56:59], v[172:175], v[200:203], v[56:59]
	v_mfma_f32_16x16x32_bf16 v[44:47], v[132:135], v[212:215], v[44:47]
	v_mfma_f32_16x16x32_bf16 v[40:43], v[172:175], v[212:215], v[40:43]
	v_mfma_f32_16x16x32_bf16 v[28:31], v[132:135], v[220:223], v[28:31]
	v_mfma_f32_16x16x32_bf16 v[24:27], v[172:175], v[220:223], v[24:27]
	v_mfma_f32_16x16x32_bf16 v[12:15], v[132:135], v[228:231], v[12:15]
	v_mfma_f32_16x16x32_bf16 v[8:11], v[172:175], v[228:231], v[8:11]
	s_setprio 0
	s_setprio 1
	v_mfma_f32_16x16x32_bf16 v[52:55], v[178:181], v[196:199], v[52:55]
	v_mfma_f32_16x16x32_bf16 v[48:51], v[188:191], v[196:199], v[48:51]
	v_mfma_f32_16x16x32_bf16 v[36:39], v[178:181], v[208:211], v[36:39]
	v_mfma_f32_16x16x32_bf16 v[32:35], v[188:191], v[208:211], v[32:35]
	v_mfma_f32_16x16x32_bf16 v[20:23], v[178:181], v[216:219], v[20:23]
	v_mfma_f32_16x16x32_bf16 v[16:19], v[188:191], v[216:219], v[16:19]
	v_mfma_f32_16x16x32_bf16 v[4:7], v[178:181], v[224:227], v[4:7]
	v_mfma_f32_16x16x32_bf16 v[0:3], v[188:191], v[224:227], v[0:3]
	v_mfma_f32_16x16x32_bf16 v[52:55], v[184:187], v[200:203], v[52:55]
	v_mfma_f32_16x16x32_bf16 v[48:51], v[192:195], v[200:203], v[48:51]
	v_mfma_f32_16x16x32_bf16 v[36:39], v[184:187], v[212:215], v[36:39]
	v_mfma_f32_16x16x32_bf16 v[32:35], v[192:195], v[212:215], v[32:35]
	v_mfma_f32_16x16x32_bf16 v[20:23], v[184:187], v[220:223], v[20:23]
	v_mfma_f32_16x16x32_bf16 v[16:19], v[192:195], v[220:223], v[16:19]
	v_mfma_f32_16x16x32_bf16 v[4:7], v[184:187], v[228:231], v[4:7]
	v_mfma_f32_16x16x32_bf16 v[0:3], v[192:195], v[228:231], v[0:3]
	s_setprio 0
	s_barrier
	s_add_i32 s76, s76, 2
	s_add_u32 s54, s54, 0x100
	s_addc_u32 s55, s55, 0
	s_add_u32 s74, s74, 0x100
	s_addc_u32 s75, s75, 0
	s_cmp_gt_u32 s76, 13
	s_cbranch_scc1 .Lpeel_exit_2

; #define PG8_BAR __builtin_amdgcn_s_barrier()
; template <class Epi, class Sched, bool ALIGN_EPI = false, bool SP2 = false>
; __device__ __forceinline__ void gemm_phase(PG8_LAS unsigned char* lds, const Gemm g, const Sched& S, const Epi& E) {
;     ...
;         if constexpr (ALIGN_EPI) { if (wr == 0) PG8_BAR; }
.Lpeel_exit_2:
	s_and_b64 vcc, exec, s[16:17]
	s_cbranch_vccz .LBB0_483
	s_barrier

; #define PG8_STAGE(bufoff, gbase, voff) do { _Pragma("unroll") for (int _i = 0; _i < 2; ++_i) \
;         __builtin_amdgcn_global_load_lds((const unsigned*)((const char*)(gbase) + (voff)[_i]), (PG8_LAS unsigned*)(lds + (bufoff) + ldsw + _i * 8192), 16, 0, 0); } while (0)
; #define PG8_LDA(dst, b, h) do { _Pragma("unroll") for (int m = 0; m < 4; ++m) _Pragma("unroll") for (int k = 0; k < 2; ++k) dst[m][k] = *(const PG8_LAS bf16x8*)(lds + PG8_SA(b, h) + aoff + m * 2048 + k * 1024); } while (0)
; #define PG8_LDB(dst, b, h) do { _Pragma("unroll") for (int n = 0; n < 2; ++n) _Pragma("unroll") for (int k = 0; k < 2; ++k) dst[n][k] = *(const PG8_LAS bf16x8*)(lds + PG8_SB(b, h) + boff + n * 2048 + k * 1024); } while (0)
; template <class Epi, class Sched, bool ALIGN_EPI = false, bool SP2 = false>
; __device__ __forceinline__ void gemm_phase(PG8_LAS unsigned char* lds, const Gemm g, const Sched& S, const Epi& E) {
;     ...
;     f32x4 acc[2][2][4][2];
; #pragma unroll
;     for (int a = 0; a < 2; ++a)
; #pragma unroll
;         for (int b = 0; b < 2; ++b)
; #pragma unroll
;             for (int m = 0; m < 4; ++m)
; #pragma unroll
;                 for (int n = 0; n < 2; ++n) acc[a][b][m][n] = (f32x4){0.f, 0.f, 0.f, 0.f};
;     ...
;         const bool has_next = S.next(ui + 1, nxt);
;         const char* nA = has_next ? (const char*)g.A + (size_t)nxt.pm * tstep : cA; const char* nB = has_next ? (const char*)g.Bt + (size_t)nxt.pn * tstep : cB;
;         for (int t = 0; t < nt; t += 2) {
;             const bool last = (t == nt - 2);
;             const char* a1 = cA + (size_t)(t + 1) * kstep;
;             const char* a2 = last ? nA : cA + (size_t)(t + 2) * kstep; const char* b2 = last ? nB : cB + (size_t)(t + 2) * kstep;
;             const char* a3 = a2 + kstep; const char* b3 = b2 + kstep;
;             if (last && has_next) S.a_ready(nxt);
;             if constexpr (SP2) {
;             PG8_LDB(B0, 0, 0); PG8_LDB(B1, 0, 1); PG8_SCHED; PG8_LDA(At, 0, 0); PG8_STAGE(PG8_SA(1, 1), a1 + hstep, voffA);
;             PG8_WAIT_V(8); PG8_WAIT_L(0); PG8_BAR; PG8_MMA(0, 0, At, B0); PG8_MMA(0, 1, At, B1); PG8_BAR; PG8_SCHED;
;             PG8_LDA(At, 0, 1); PG8_STAGE(PG8_SB(0, 0), b2, voffB); PG8_STAGE(PG8_SB(0, 1), b2 + hstep, voffB); PG8_STAGE(PG8_SA(0, 0), a2, voffA);
;             PG8_WAIT_V(8); PG8_WAIT_L(0); PG8_BAR; PG8_MMA(1, 0, At, B0); PG8_MMA(1, 1, At, B1); PG8_BAR; PG8_SCHED;
.LBB0_566:
	s_ashr_i32 s17, s16, 31
	s_lshl_b64 s[40:41], s[16:17], 19
	s_add_u32 s40, s36, s40
	s_addc_u32 s41, s37, s41
	s_and_b64 s[42:43], s[2:3], exec
	s_cselect_b32 s62, s41, s1
	s_cselect_b32 s63, s40, s0
	s_ashr_i32 s13, s12, 31
	s_lshl_b64 s[42:43], s[12:13], 19
	s_add_u32 s42, s20, s42
	s_addc_u32 s43, s21, s43
	s_and_b64 s[48:49], s[2:3], exec
	s_cselect_b32 s13, s43, s47
	s_cselect_b32 s64, s42, s46
	s_add_u32 s0, s0, 0x40080
	s_addc_u32 s1, s1, 0
	s_add_u32 s65, s46, 0x100
	s_addc_u32 s66, s47, 0
	s_mov_b32 s67, -2
	ds_read_b128 v[156:159], v150
	ds_read_b128 v[160:163], v150 offset:1024
	ds_read_b128 v[164:167], v150 offset:2048
	ds_read_b128 v[168:171], v150 offset:3072
	ds_read_b128 v[172:175], v151
	ds_read_b128 v[176:179], v151 offset:1024
	ds_read_b128 v[180:183], v151 offset:2048
	ds_read_b128 v[184:187], v151 offset:3072
	s_add_u32 s19, s0, 0xfffc0080
	s_addc_u32 s46, s1, -1
	s_cmp_eq_u32 s67, 12
	s_cselect_b32 s49, s62, s46
	s_cselect_b32 s48, s63, s19
	s_cselect_b32 s47, s13, s66
	s_cselect_b32 s46, s64, s65
	v_lshl_add_u64 v[204:205], s[0:1], 0, v[138:139]
	s_add_i32 m0, s33, 0xc000
	ds_read_b128 v[188:191], v152
	ds_read_b128 v[192:195], v152 offset:1024
	ds_read_b128 v[196:199], v152 offset:2048
	ds_read_b128 v[200:203], v152 offset:3072
	ds_read_b128 v[208:211], v152 offset:4096
	ds_read_b128 v[212:215], v152 offset:5120
	ds_read_b128 v[216:219], v152 offset:6144
	ds_read_b128 v[220:223], v152 offset:7168
	global_load_lds_dwordx4 v[204:205], off
	v_lshl_add_u64 v[204:205], s[0:1], 0, v[140:141]
	s_add_i32 m0, s33, 0xe000
	s_nop 0
	global_load_lds_dwordx4 v[204:205], off
	s_waitcnt vmcnt(8)
	s_waitcnt lgkmcnt(0)
	s_barrier
	s_setprio 1
	s_waitcnt lgkmcnt(0)
	v_mfma_f32_16x16x32_bf16 v[124:127], v[156:159], v[188:191], 0
	v_mfma_f32_16x16x32_bf16 v[116:119], v[164:167], v[188:191], 0
	v_mfma_f32_16x16x32_bf16 v[108:111], v[156:159], v[196:199], 0
	v_mfma_f32_16x16x32_bf16 v[100:103], v[164:167], v[196:199], 0
	v_mfma_f32_16x16x32_bf16 v[92:95], v[156:159], v[208:211], 0
	v_mfma_f32_16x16x32_bf16 v[84:87], v[164:167], v[208:211], 0
	v_mfma_f32_16x16x32_bf16 v[76:79], v[156:159], v[216:219], 0
	v_mfma_f32_16x16x32_bf16 v[68:71], v[164:167], v[216:219], 0
	v_mfma_f32_16x16x32_bf16 v[124:127], v[160:163], v[192:195], v[124:127]
	v_mfma_f32_16x16x32_bf16 v[116:119], v[168:171], v[192:195], v[116:119]
	v_mfma_f32_16x16x32_bf16 v[108:111], v[160:163], v[200:203], v[108:111]
	v_mfma_f32_16x16x32_bf16 v[100:103], v[168:171], v[200:203], v[100:103]
	v_mfma_f32_16x16x32_bf16 v[92:95], v[160:163], v[212:215], v[92:95]
	v_mfma_f32_16x16x32_bf16 v[84:87], v[168:171], v[212:215], v[84:87]
	v_mfma_f32_16x16x32_bf16 v[76:79], v[160:163], v[220:223], v[76:79]
	v_mfma_f32_16x16x32_bf16 v[68:71], v[168:171], v[220:223], v[68:71]
	s_setprio 0
	s_setprio 1
	v_mfma_f32_16x16x32_bf16 v[120:123], v[172:175], v[188:191], 0
	v_mfma_f32_16x16x32_bf16 v[112:115], v[180:183], v[188:191], 0
	v_mfma_f32_16x16x32_bf16 v[104:107], v[172:175], v[196:199], 0
	v_mfma_f32_16x16x32_bf16 v[96:99], v[180:183], v[196:199], 0
	v_mfma_f32_16x16x32_bf16 v[88:91], v[172:175], v[208:211], 0
	v_mfma_f32_16x16x32_bf16 v[80:83], v[180:183], v[208:211], 0
	v_mfma_f32_16x16x32_bf16 v[72:75], v[172:175], v[216:219], 0
	v_mfma_f32_16x16x32_bf16 v[64:67], v[180:183], v[216:219], 0
	v_mfma_f32_16x16x32_bf16 v[120:123], v[176:179], v[192:195], v[120:123]
	v_mfma_f32_16x16x32_bf16 v[112:115], v[184:187], v[192:195], v[112:115]
	v_mfma_f32_16x16x32_bf16 v[104:107], v[176:179], v[200:203], v[104:107]
	v_mfma_f32_16x16x32_bf16 v[96:99], v[184:187], v[200:203], v[96:99]
	v_mfma_f32_16x16x32_bf16 v[88:91], v[176:179], v[212:215], v[88:91]
	v_mfma_f32_16x16x32_bf16 v[80:83], v[184:187], v[212:215], v[80:83]
	v_mfma_f32_16x16x32_bf16 v[72:75], v[176:179], v[220:223], v[72:75]
	v_mfma_f32_16x16x32_bf16 v[64:67], v[184:187], v[220:223], v[64:67]
	s_setprio 0
	s_barrier
	s_add_i32 s19, s55, s14
	v_lshl_add_u64 v[204:205], s[46:47], 0, v[132:133]
	s_mov_b32 m0, s19
	ds_read_b128 v[188:191], v152 offset:16384
	ds_read_b128 v[192:195], v152 offset:17408
	ds_read_b128 v[196:199], v152 offset:18432
	ds_read_b128 v[200:203], v152 offset:19456
	ds_read_b128 v[208:211], v152 offset:20480
	ds_read_b128 v[212:215], v152 offset:21504
	ds_read_b128 v[216:219], v152 offset:22528
	ds_read_b128 v[220:223], v152 offset:23552
	global_load_lds_dwordx4 v[204:205], off
	s_add_i32 m0, s19, 0x2000
	s_add_u32 s70, s46, 0x40000
	v_lshl_add_u64 v[224:225], s[46:47], 0, v[128:129]
	s_addc_u32 s71, s47, 0
	s_add_i32 s19, s56, s14
	global_load_lds_dwordx4 v[224:225], off
	v_lshl_add_u64 v[226:227], s[70:71], 0, v[132:133]
	s_mov_b32 m0, s19
	v_lshl_add_u64 v[228:229], s[48:49], 0, v[130:131]
	global_load_lds_dwordx4 v[226:227], off
	v_lshl_add_u64 v[226:227], s[70:71], 0, v[128:129]
	s_add_i32 m0, s19, 0x2000
	s_nop 0
	global_load_lds_dwordx4 v[226:227], off
	v_lshl_add_u64 v[226:227], s[48:49], 0, v[134:135]
	s_mov_b32 m0, s33
	s_nop 0
	global_load_lds_dwordx4 v[226:227], off
	s_mov_b32 m0, s35
	s_nop 0
	global_load_lds_dwordx4 v[228:229], off
	s_waitcnt vmcnt(8)
	s_waitcnt lgkmcnt(0)
	s_barrier
; #define PG8_STAGE(bufoff, gbase, voff) do { _Pragma("unroll") for (int _i = 0; _i < 2; ++_i) \
;         __builtin_amdgcn_global_load_lds((const unsigned*)((const char*)(gbase) + (voff)[_i]), (PG8_LAS unsigned*)(lds + (bufoff) + ldsw + _i * 8192), 16, 0, 0); } while (0)
; #define PG8_LDA(dst, b, h) do { _Pragma("unroll") for (int m = 0; m < 4; ++m) _Pragma("unroll") for (int k = 0; k < 2; ++k) dst[m][k] = *(const PG8_LAS bf16x8*)(lds + PG8_SA(b, h) + aoff + m * 2048 + k * 1024); } while (0)
; #define PG8_LDB(dst, b, h) do { _Pragma("unroll") for (int n = 0; n < 2; ++n) _Pragma("unroll") for (int k = 0; k < 2; ++k) dst[n][k] = *(const PG8_LAS bf16x8*)(lds + PG8_SB(b, h) + boff + n * 2048 + k * 1024); } while (0)
; #define PG8_MMA(ai, bj, At, Bt) do { __builtin_amdgcn_s_setprio(1); _Pragma("unroll") for (int m = 0; m < 4; ++m) _Pragma("unroll") for (int n = 0; n < 2; ++n) _Pragma("unroll") for (int k = 0; k < 2; ++k) \
;         acc[ai][bj][m][n] = __builtin_amdgcn_mfma_f32_16x16x32_bf16(Bt[n][k], At[m][k], acc[ai][bj][m][n], 0, 0, 0); __builtin_amdgcn_s_setprio(0); } while (0)
; #define PG8_WAIT_V(n) asm volatile("s_waitcnt vmcnt(" #n ")" ::: "memory")
; #define PG8_WAIT_L(n) asm volatile("s_waitcnt lgkmcnt(" #n ")" ::: "memory")
; #define PG8_BAR __builtin_amdgcn_s_barrier()
; #define PG8_SCHED __builtin_amdgcn_sched_barrier(0)
; template <class Epi, class Sched, bool ALIGN_EPI = false, bool SP2 = false>
; __device__ __forceinline__ void gemm_phase(PG8_LAS unsigned char* lds, const Gemm g, const Sched& S, const Epi& E) {
;     ...
;             PG8_WAIT_V(8); PG8_WAIT_L(0); PG8_BAR; PG8_MMA(1, 0, At, B0); PG8_MMA(1, 1, At, B1); PG8_BAR; PG8_SCHED;
;             PG8_LDB(B0, 1, 0); PG8_LDB(B1, 1, 1); PG8_SCHED; PG8_LDA(At, 1, 0); PG8_STAGE(PG8_SA(0, 1), a2 + hstep, voffA);
;             PG8_WAIT_V(8); PG8_WAIT_L(0); PG8_BAR; PG8_MMA(0, 0, At, B0); PG8_MMA(0, 1, At, B1); PG8_BAR; PG8_SCHED;
	s_setprio 1
	s_waitcnt lgkmcnt(0)
	v_mfma_f32_16x16x32_bf16 v[60:63], v[156:159], v[188:191], 0
	v_mfma_f32_16x16x32_bf16 v[52:55], v[164:167], v[188:191], 0
	v_mfma_f32_16x16x32_bf16 v[44:47], v[156:159], v[196:199], 0
	v_mfma_f32_16x16x32_bf16 v[36:39], v[164:167], v[196:199], 0
	v_mfma_f32_16x16x32_bf16 v[28:31], v[156:159], v[208:211], 0
	v_mfma_f32_16x16x32_bf16 v[20:23], v[164:167], v[208:211], 0
	v_mfma_f32_16x16x32_bf16 v[12:15], v[156:159], v[216:219], 0
	v_mfma_f32_16x16x32_bf16 v[4:7], v[164:167], v[216:219], 0
	v_mfma_f32_16x16x32_bf16 v[60:63], v[160:163], v[192:195], v[60:63]
	v_mfma_f32_16x16x32_bf16 v[52:55], v[168:171], v[192:195], v[52:55]
	v_mfma_f32_16x16x32_bf16 v[44:47], v[160:163], v[200:203], v[44:47]
	v_mfma_f32_16x16x32_bf16 v[36:39], v[168:171], v[200:203], v[36:39]
	v_mfma_f32_16x16x32_bf16 v[28:31], v[160:163], v[212:215], v[28:31]
	v_mfma_f32_16x16x32_bf16 v[20:23], v[168:171], v[212:215], v[20:23]
	v_mfma_f32_16x16x32_bf16 v[12:15], v[160:163], v[220:223], v[12:15]
	v_mfma_f32_16x16x32_bf16 v[4:7], v[168:171], v[220:223], v[4:7]
	s_setprio 0
	s_setprio 1
	v_mfma_f32_16x16x32_bf16 v[56:59], v[172:175], v[188:191], 0
	v_mfma_f32_16x16x32_bf16 v[48:51], v[180:183], v[188:191], 0
	v_mfma_f32_16x16x32_bf16 v[40:43], v[172:175], v[196:199], 0
	v_mfma_f32_16x16x32_bf16 v[32:35], v[180:183], v[196:199], 0
	v_mfma_f32_16x16x32_bf16 v[24:27], v[172:175], v[208:211], 0
	v_mfma_f32_16x16x32_bf16 v[16:19], v[180:183], v[208:211], 0
	v_mfma_f32_16x16x32_bf16 v[8:11], v[172:175], v[216:219], 0
	v_mfma_f32_16x16x32_bf16 v[0:3], v[180:183], v[216:219], 0
	v_mfma_f32_16x16x32_bf16 v[56:59], v[176:179], v[192:195], v[56:59]
	v_mfma_f32_16x16x32_bf16 v[48:51], v[184:187], v[192:195], v[48:51]
	v_mfma_f32_16x16x32_bf16 v[40:43], v[176:179], v[200:203], v[40:43]
	v_mfma_f32_16x16x32_bf16 v[32:35], v[184:187], v[200:203], v[32:35]
	v_mfma_f32_16x16x32_bf16 v[24:27], v[176:179], v[212:215], v[24:27]
	v_mfma_f32_16x16x32_bf16 v[16:19], v[184:187], v[212:215], v[16:19]
	v_mfma_f32_16x16x32_bf16 v[8:11], v[176:179], v[220:223], v[8:11]
	v_mfma_f32_16x16x32_bf16 v[0:3], v[184:187], v[220:223], v[0:3]
	s_setprio 0
	s_barrier
	s_add_i32 s19, 0, 0x18000
	v_add_u32_e32 v155, s19, v147
	s_add_i32 s70, 0, 0x1c000
	ds_read_b128 v[156:159], v155
	ds_read_b128 v[160:163], v155 offset:1024
	ds_read_b128 v[164:167], v155 offset:2048
	ds_read_b128 v[168:171], v155 offset:3072
	v_add_u32_e32 v155, s70, v147
	ds_read_b128 v[172:175], v155
	ds_read_b128 v[176:179], v155 offset:1024
	ds_read_b128 v[180:183], v155 offset:2048
	ds_read_b128 v[184:187], v155 offset:3072
	s_add_u32 s48, s48, 0x40000
	s_addc_u32 s49, s49, 0
	s_mov_b32 m0, s45
	v_lshl_add_u64 v[230:231], s[48:49], 0, v[134:135]
	ds_read_b128 v[188:191], v152 offset:32768
	ds_read_b128 v[192:195], v152 offset:33792
	ds_read_b128 v[196:199], v152 offset:34816
	ds_read_b128 v[200:203], v152 offset:35840
	ds_read_b128 v[208:211], v152 offset:36864
	ds_read_b128 v[212:215], v152 offset:37888
	ds_read_b128 v[216:219], v152 offset:38912
	ds_read_b128 v[220:223], v152 offset:39936
	global_load_lds_dwordx4 v[230:231], off
	v_lshl_add_u64 v[230:231], s[48:49], 0, v[130:131]
	s_mov_b32 m0, s50
	s_nop 0
	global_load_lds_dwordx4 v[230:231], off
	s_waitcnt vmcnt(8)
	s_waitcnt lgkmcnt(0)
	s_barrier
	s_setprio 1
	s_waitcnt lgkmcnt(0)
	v_mfma_f32_16x16x32_bf16 v[124:127], v[156:159], v[188:191], v[124:127]
	v_mfma_f32_16x16x32_bf16 v[116:119], v[164:167], v[188:191], v[116:119]
	v_mfma_f32_16x16x32_bf16 v[108:111], v[156:159], v[196:199], v[108:111]
	v_mfma_f32_16x16x32_bf16 v[100:103], v[164:167], v[196:199], v[100:103]
	v_mfma_f32_16x16x32_bf16 v[92:95], v[156:159], v[208:211], v[92:95]
	v_mfma_f32_16x16x32_bf16 v[84:87], v[164:167], v[208:211], v[84:87]
	v_mfma_f32_16x16x32_bf16 v[76:79], v[156:159], v[216:219], v[76:79]
	v_mfma_f32_16x16x32_bf16 v[68:71], v[164:167], v[216:219], v[68:71]
	v_mfma_f32_16x16x32_bf16 v[124:127], v[160:163], v[192:195], v[124:127]
	v_mfma_f32_16x16x32_bf16 v[116:119], v[168:171], v[192:195], v[116:119]
	v_mfma_f32_16x16x32_bf16 v[108:111], v[160:163], v[200:203], v[108:111]
	v_mfma_f32_16x16x32_bf16 v[100:103], v[168:171], v[200:203], v[100:103]
	v_mfma_f32_16x16x32_bf16 v[92:95], v[160:163], v[212:215], v[92:95]
	v_mfma_f32_16x16x32_bf16 v[84:87], v[168:171], v[212:215], v[84:87]
	v_mfma_f32_16x16x32_bf16 v[76:79], v[160:163], v[220:223], v[76:79]
	v_mfma_f32_16x16x32_bf16 v[68:71], v[168:171], v[220:223], v[68:71]
	s_setprio 0
	s_setprio 1
	v_mfma_f32_16x16x32_bf16 v[120:123], v[172:175], v[188:191], v[120:123]
	v_mfma_f32_16x16x32_bf16 v[112:115], v[180:183], v[188:191], v[112:115]
	v_mfma_f32_16x16x32_bf16 v[104:107], v[172:175], v[196:199], v[104:107]
	v_mfma_f32_16x16x32_bf16 v[96:99], v[180:183], v[196:199], v[96:99]
	v_mfma_f32_16x16x32_bf16 v[88:91], v[172:175], v[208:211], v[88:91]
	v_mfma_f32_16x16x32_bf16 v[80:83], v[180:183], v[208:211], v[80:83]
	v_mfma_f32_16x16x32_bf16 v[72:75], v[172:175], v[216:219], v[72:75]
	v_mfma_f32_16x16x32_bf16 v[64:67], v[180:183], v[216:219], v[64:67]
	v_mfma_f32_16x16x32_bf16 v[120:123], v[176:179], v[192:195], v[120:123]
	v_mfma_f32_16x16x32_bf16 v[112:115], v[184:187], v[192:195], v[112:115]
	v_mfma_f32_16x16x32_bf16 v[104:107], v[176:179], v[200:203], v[104:107]
	v_mfma_f32_16x16x32_bf16 v[96:99], v[184:187], v[200:203], v[96:99]
	v_mfma_f32_16x16x32_bf16 v[88:91], v[176:179], v[212:215], v[88:91]
	v_mfma_f32_16x16x32_bf16 v[80:83], v[184:187], v[212:215], v[80:83]
	v_mfma_f32_16x16x32_bf16 v[72:75], v[176:179], v[220:223], v[72:75]
	v_mfma_f32_16x16x32_bf16 v[64:67], v[184:187], v[220:223], v[64:67]
	s_setprio 0
	s_barrier
; #define PG8_STAGE(bufoff, gbase, voff) do { _Pragma("unroll") for (int _i = 0; _i < 2; ++_i) \
;         __builtin_amdgcn_global_load_lds((const unsigned*)((const char*)(gbase) + (voff)[_i]), (PG8_LAS unsigned*)(lds + (bufoff) + ldsw + _i * 8192), 16, 0, 0); } while (0)
; #define PG8_LDA(dst, b, h) do { _Pragma("unroll") for (int m = 0; m < 4; ++m) _Pragma("unroll") for (int k = 0; k < 2; ++k) dst[m][k] = *(const PG8_LAS bf16x8*)(lds + PG8_SA(b, h) + aoff + m * 2048 + k * 1024); } while (0)
; #define PG8_MMA(ai, bj, At, Bt) do { __builtin_amdgcn_s_setprio(1); _Pragma("unroll") for (int m = 0; m < 4; ++m) _Pragma("unroll") for (int n = 0; n < 2; ++n) _Pragma("unroll") for (int k = 0; k < 2; ++k) \
;         acc[ai][bj][m][n] = __builtin_amdgcn_mfma_f32_16x16x32_bf16(Bt[n][k], At[m][k], acc[ai][bj][m][n], 0, 0, 0); __builtin_amdgcn_s_setprio(0); } while (0)
; #define PG8_WAIT_V(n) asm volatile("s_waitcnt vmcnt(" #n ")" ::: "memory")
; #define PG8_WAIT_L(n) asm volatile("s_waitcnt lgkmcnt(" #n ")" ::: "memory")
; #define PG8_BAR __builtin_amdgcn_s_barrier()
; #define PG8_SCHED __builtin_amdgcn_sched_barrier(0)
; template <class Epi, class Sched, bool ALIGN_EPI = false, bool SP2 = false>
; __device__ __forceinline__ void gemm_phase(PG8_LAS unsigned char* lds, const Gemm g, const Sched& S, const Epi& E) {
;     ...
;         for (int t = 0; t < nt; t += 2) {
;             const bool last = (t == nt - 2);
;     ...
;             PG8_LDA(At, 1, 1); PG8_STAGE(PG8_SB(1, 0), b3, voffB); PG8_STAGE(PG8_SB(1, 1), b3 + hstep, voffB); PG8_STAGE(PG8_SA(1, 0), a3, voffA);
;             PG8_WAIT_V(8); PG8_WAIT_L(0); PG8_BAR; PG8_MMA(1, 0, At, B0); PG8_MMA(1, 1, At, B1); PG8_BAR; PG8_SCHED;
	s_add_i32 s19, s19, s14
	v_lshl_add_u64 v[204:205], v[204:205], 0, s[8:9]
	s_mov_b32 m0, s19
	ds_read_b128 v[188:191], v152 offset:49152
	ds_read_b128 v[192:195], v152 offset:50176
	ds_read_b128 v[196:199], v152 offset:51200
	ds_read_b128 v[200:203], v152 offset:52224
	ds_read_b128 v[208:211], v152 offset:53248
	ds_read_b128 v[212:215], v152 offset:54272
	ds_read_b128 v[216:219], v152 offset:55296
	ds_read_b128 v[220:223], v152 offset:56320
	global_load_lds_dwordx4 v[204:205], off
	s_add_i32 m0, s19, 0x2000
	s_add_u32 s46, s46, 0x40080
	v_lshl_add_u64 v[204:205], v[224:225], 0, s[8:9]
	s_addc_u32 s47, s47, 0
	s_add_i32 s19, s70, s14
	global_load_lds_dwordx4 v[204:205], off
	v_lshl_add_u64 v[204:205], s[46:47], 0, v[132:133]
	s_mov_b32 m0, s19
	s_nop 0
	global_load_lds_dwordx4 v[204:205], off
	v_lshl_add_u64 v[204:205], s[46:47], 0, v[128:129]
	s_add_i32 m0, s19, 0x2000
	s_nop 0
	global_load_lds_dwordx4 v[204:205], off
	v_lshl_add_u64 v[204:205], v[226:227], 0, s[8:9]
	s_mov_b32 m0, s51
	s_nop 0
	global_load_lds_dwordx4 v[204:205], off
	v_lshl_add_u64 v[204:205], v[228:229], 0, s[8:9]
	s_mov_b32 m0, s52
	s_nop 0
	global_load_lds_dwordx4 v[204:205], off
	s_waitcnt vmcnt(8)
	s_waitcnt lgkmcnt(0)
	s_barrier
	s_setprio 1
	s_waitcnt lgkmcnt(0)
	v_mfma_f32_16x16x32_bf16 v[60:63], v[156:159], v[188:191], v[60:63]
	v_mfma_f32_16x16x32_bf16 v[52:55], v[164:167], v[188:191], v[52:55]
	v_mfma_f32_16x16x32_bf16 v[44:47], v[156:159], v[196:199], v[44:47]
	v_mfma_f32_16x16x32_bf16 v[36:39], v[164:167], v[196:199], v[36:39]
	v_mfma_f32_16x16x32_bf16 v[28:31], v[156:159], v[208:211], v[28:31]
	v_mfma_f32_16x16x32_bf16 v[20:23], v[164:167], v[208:211], v[20:23]
	v_mfma_f32_16x16x32_bf16 v[12:15], v[156:159], v[216:219], v[12:15]
	v_mfma_f32_16x16x32_bf16 v[4:7], v[164:167], v[216:219], v[4:7]
	v_mfma_f32_16x16x32_bf16 v[60:63], v[160:163], v[192:195], v[60:63]
	v_mfma_f32_16x16x32_bf16 v[52:55], v[168:171], v[192:195], v[52:55]
	v_mfma_f32_16x16x32_bf16 v[44:47], v[160:163], v[200:203], v[44:47]
	v_mfma_f32_16x16x32_bf16 v[36:39], v[168:171], v[200:203], v[36:39]
	v_mfma_f32_16x16x32_bf16 v[28:31], v[160:163], v[212:215], v[28:31]
	v_mfma_f32_16x16x32_bf16 v[20:23], v[168:171], v[212:215], v[20:23]
	v_mfma_f32_16x16x32_bf16 v[12:15], v[160:163], v[220:223], v[12:15]
	v_mfma_f32_16x16x32_bf16 v[4:7], v[168:171], v[220:223], v[4:7]
	s_setprio 0
	s_setprio 1
	v_mfma_f32_16x16x32_bf16 v[56:59], v[172:175], v[188:191], v[56:59]
	v_mfma_f32_16x16x32_bf16 v[48:51], v[180:183], v[188:191], v[48:51]
	v_mfma_f32_16x16x32_bf16 v[40:43], v[172:175], v[196:199], v[40:43]
	v_mfma_f32_16x16x32_bf16 v[32:35], v[180:183], v[196:199], v[32:35]
	v_mfma_f32_16x16x32_bf16 v[24:27], v[172:175], v[208:211], v[24:27]
	v_mfma_f32_16x16x32_bf16 v[16:19], v[180:183], v[208:211], v[16:19]
	v_mfma_f32_16x16x32_bf16 v[8:11], v[172:175], v[216:219], v[8:11]
	v_mfma_f32_16x16x32_bf16 v[0:3], v[180:183], v[216:219], v[0:3]
	v_mfma_f32_16x16x32_bf16 v[56:59], v[176:179], v[192:195], v[56:59]
	v_mfma_f32_16x16x32_bf16 v[48:51], v[184:187], v[192:195], v[48:51]
	v_mfma_f32_16x16x32_bf16 v[40:43], v[176:179], v[200:203], v[40:43]
	v_mfma_f32_16x16x32_bf16 v[32:35], v[184:187], v[200:203], v[32:35]
	v_mfma_f32_16x16x32_bf16 v[24:27], v[176:179], v[212:215], v[24:27]
	v_mfma_f32_16x16x32_bf16 v[16:19], v[184:187], v[212:215], v[16:19]
	v_mfma_f32_16x16x32_bf16 v[8:11], v[176:179], v[220:223], v[8:11]
	v_mfma_f32_16x16x32_bf16 v[0:3], v[184:187], v[220:223], v[0:3]
	s_setprio 0
	s_barrier
	s_add_i32 s67, s67, 2
	s_add_u32 s0, s0, 0x100
	s_addc_u32 s1, s1, 0
	s_add_u32 s65, s65, 0x100
	s_addc_u32 s66, s66, 0
	s_cmp_gt_u32 s67, 13
	s_cbranch_scc1 .Lpeel_exit_3

; #define PG8_STAGE(bufoff, gbase, voff) do { _Pragma("unroll") for (int _i = 0; _i < 2; ++_i) \
;         __builtin_amdgcn_global_load_lds((const unsigned*)((const char*)(gbase) + (voff)[_i]), (PG8_LAS unsigned*)(lds + (bufoff) + ldsw + _i * 8192), 16, 0, 0); } while (0)
; #define PG8_LDA(dst, b, h) do { _Pragma("unroll") for (int m = 0; m < 4; ++m) _Pragma("unroll") for (int k = 0; k < 2; ++k) dst[m][k] = *(const PG8_LAS bf16x8*)(lds + PG8_SA(b, h) + aoff + m * 2048 + k * 1024); } while (0)
; #define PG8_LDB(dst, b, h) do { _Pragma("unroll") for (int n = 0; n < 2; ++n) _Pragma("unroll") for (int k = 0; k < 2; ++k) dst[n][k] = *(const PG8_LAS bf16x8*)(lds + PG8_SB(b, h) + boff + n * 2048 + k * 1024); } while (0)
; template <class Epi, class Sched, bool ALIGN_EPI = false, bool SP2 = false>
; __device__ __forceinline__ void gemm_phase(PG8_LAS unsigned char* lds, const Gemm g, const Sched& S, const Epi& E) {
;     ...
;     f32x4 acc[2][2][4][2];
; #pragma unroll
;     for (int a = 0; a < 2; ++a)
; #pragma unroll
;         for (int b = 0; b < 2; ++b)
; #pragma unroll
;             for (int m = 0; m < 4; ++m)
; #pragma unroll
;                 for (int n = 0; n < 2; ++n) acc[a][b][m][n] = (f32x4){0.f, 0.f, 0.f, 0.f};
;     ...
;         const bool has_next = S.next(ui + 1, nxt);
;         const char* nA = has_next ? (const char*)g.A + (size_t)nxt.pm * tstep : cA; const char* nB = has_next ? (const char*)g.Bt + (size_t)nxt.pn * tstep : cB;
;         for (int t = 0; t < nt; t += 2) {
;             const bool last = (t == nt - 2);
;             const char* a1 = cA + (size_t)(t + 1) * kstep;
;             const char* a2 = last ? nA : cA + (size_t)(t + 2) * kstep; const char* b2 = last ? nB : cB + (size_t)(t + 2) * kstep;
;             const char* a3 = a2 + kstep; const char* b3 = b2 + kstep;
;             if (last && has_next) S.a_ready(nxt);
;             if constexpr (SP2) {
;             PG8_LDB(B0, 0, 0); PG8_LDB(B1, 0, 1); PG8_SCHED; PG8_LDA(At, 0, 0); PG8_STAGE(PG8_SA(1, 1), a1 + hstep, voffA);
;             PG8_WAIT_V(8); PG8_WAIT_L(0); PG8_BAR; PG8_MMA(0, 0, At, B0); PG8_MMA(0, 1, At, B1); PG8_BAR; PG8_SCHED;
;             PG8_LDA(At, 0, 1); PG8_STAGE(PG8_SB(0, 0), b2, voffB); PG8_STAGE(PG8_SB(0, 1), b2 + hstep, voffB); PG8_STAGE(PG8_SA(0, 0), a2, voffA);
;             PG8_WAIT_V(8); PG8_WAIT_L(0); PG8_BAR; PG8_MMA(1, 0, At, B0); PG8_MMA(1, 1, At, B1); PG8_BAR; PG8_SCHED;
.LBB0_682:
	s_add_u32 s0, s8, 0xb0080
	s_addc_u32 s1, s9, 0
	s_add_u32 s12, s6, 0x100
	s_addc_u32 s13, s7, 0
	s_mov_b32 s16, -2
	ds_read_b128 v[128:131], v199
	ds_read_b128 v[132:135], v199 offset:1024
	ds_read_b128 v[152:155], v199 offset:2048
	ds_read_b128 v[156:159], v199 offset:3072
	ds_read_b128 v[160:163], v200
	ds_read_b128 v[164:167], v200 offset:1024
	ds_read_b128 v[168:171], v200 offset:2048
	ds_read_b128 v[172:175], v200 offset:3072
	s_add_u32 s6, s0, 0xfff50080
	s_addc_u32 s7, s1, -1
	s_cmp_eq_u32 s16, 40
	s_cselect_b32 s9, s59, s7
	s_cselect_b32 s8, s58, s6
	s_cselect_b32 s7, s61, s13
	s_cselect_b32 s6, s60, s12
	v_lshl_add_u64 v[220:221], s[0:1], 0, v[144:145]
	s_add_i32 m0, s15, 0xc000
	ds_read_b128 v[176:179], v201
	ds_read_b128 v[180:183], v201 offset:1024
	ds_read_b128 v[184:187], v201 offset:2048
	ds_read_b128 v[188:191], v201 offset:3072
	ds_read_b128 v[192:195], v201 offset:4096
	ds_read_b128 v[208:211], v201 offset:5120
	ds_read_b128 v[212:215], v201 offset:6144
	ds_read_b128 v[216:219], v201 offset:7168
	global_load_lds_dwordx4 v[220:221], off
	v_lshl_add_u64 v[220:221], s[0:1], 0, v[146:147]
	s_add_i32 m0, s15, 0xe000
	s_nop 0
	global_load_lds_dwordx4 v[220:221], off
	s_waitcnt vmcnt(8)
	s_waitcnt lgkmcnt(0)
	s_barrier
	s_setprio 1
	s_waitcnt lgkmcnt(0)
	v_mfma_f32_16x16x32_bf16 v[124:127], v[128:131], v[176:179], 0
	v_mfma_f32_16x16x32_bf16 v[120:123], v[152:155], v[176:179], 0
	v_mfma_f32_16x16x32_bf16 v[108:111], v[128:131], v[184:187], 0
	v_mfma_f32_16x16x32_bf16 v[104:107], v[152:155], v[184:187], 0
	v_mfma_f32_16x16x32_bf16 v[92:95], v[128:131], v[192:195], 0
	v_mfma_f32_16x16x32_bf16 v[88:91], v[152:155], v[192:195], 0
	v_mfma_f32_16x16x32_bf16 v[76:79], v[128:131], v[212:215], 0
	v_mfma_f32_16x16x32_bf16 v[72:75], v[152:155], v[212:215], 0
	v_mfma_f32_16x16x32_bf16 v[124:127], v[132:135], v[180:183], v[124:127]
	v_mfma_f32_16x16x32_bf16 v[120:123], v[156:159], v[180:183], v[120:123]
	v_mfma_f32_16x16x32_bf16 v[108:111], v[132:135], v[188:191], v[108:111]
	v_mfma_f32_16x16x32_bf16 v[104:107], v[156:159], v[188:191], v[104:107]
	v_mfma_f32_16x16x32_bf16 v[92:95], v[132:135], v[208:211], v[92:95]
	v_mfma_f32_16x16x32_bf16 v[88:91], v[156:159], v[208:211], v[88:91]
	v_mfma_f32_16x16x32_bf16 v[76:79], v[132:135], v[216:219], v[76:79]
	v_mfma_f32_16x16x32_bf16 v[72:75], v[156:159], v[216:219], v[72:75]
	s_setprio 0
	s_setprio 1
	v_mfma_f32_16x16x32_bf16 v[116:119], v[160:163], v[176:179], 0
	v_mfma_f32_16x16x32_bf16 v[112:115], v[168:171], v[176:179], 0
	v_mfma_f32_16x16x32_bf16 v[100:103], v[160:163], v[184:187], 0
	v_mfma_f32_16x16x32_bf16 v[96:99], v[168:171], v[184:187], 0
	v_mfma_f32_16x16x32_bf16 v[84:87], v[160:163], v[192:195], 0
	v_mfma_f32_16x16x32_bf16 v[80:83], v[168:171], v[192:195], 0
	v_mfma_f32_16x16x32_bf16 v[68:71], v[160:163], v[212:215], 0
	v_mfma_f32_16x16x32_bf16 v[64:67], v[168:171], v[212:215], 0
	v_mfma_f32_16x16x32_bf16 v[116:119], v[164:167], v[180:183], v[116:119]
	v_mfma_f32_16x16x32_bf16 v[112:115], v[172:175], v[180:183], v[112:115]
	v_mfma_f32_16x16x32_bf16 v[100:103], v[164:167], v[188:191], v[100:103]
	v_mfma_f32_16x16x32_bf16 v[96:99], v[172:175], v[188:191], v[96:99]
	v_mfma_f32_16x16x32_bf16 v[84:87], v[164:167], v[208:211], v[84:87]
	v_mfma_f32_16x16x32_bf16 v[80:83], v[172:175], v[208:211], v[80:83]
	v_mfma_f32_16x16x32_bf16 v[68:71], v[164:167], v[216:219], v[68:71]
	v_mfma_f32_16x16x32_bf16 v[64:67], v[172:175], v[216:219], v[64:67]
	s_setprio 0
	s_barrier
	s_add_i32 s17, s64, s14
	v_lshl_add_u64 v[220:221], s[6:7], 0, v[138:139]
	s_mov_b32 m0, s17
	ds_read_b128 v[176:179], v201 offset:16384
	ds_read_b128 v[180:183], v201 offset:17408
	ds_read_b128 v[184:187], v201 offset:18432
	ds_read_b128 v[188:191], v201 offset:19456
	ds_read_b128 v[192:195], v201 offset:20480
	ds_read_b128 v[208:211], v201 offset:21504
	ds_read_b128 v[212:215], v201 offset:22528
	ds_read_b128 v[216:219], v201 offset:23552
	global_load_lds_dwordx4 v[220:221], off
	s_add_i32 m0, s17, 0x2000
	s_add_u32 s20, s6, 0xb0000
	v_lshl_add_u64 v[222:223], s[6:7], 0, v[142:143]
	s_addc_u32 s21, s7, 0
	s_add_i32 s17, s65, s14
	global_load_lds_dwordx4 v[222:223], off
	v_lshl_add_u64 v[224:225], s[20:21], 0, v[138:139]
	s_mov_b32 m0, s17
	v_lshl_add_u64 v[226:227], s[8:9], 0, v[140:141]
	global_load_lds_dwordx4 v[224:225], off
	v_lshl_add_u64 v[224:225], s[20:21], 0, v[142:143]
	s_add_i32 m0, s17, 0x2000
	s_nop 0
	global_load_lds_dwordx4 v[224:225], off
	v_lshl_add_u64 v[224:225], s[8:9], 0, v[136:137]
	s_mov_b32 m0, s15
	s_nop 0
	global_load_lds_dwordx4 v[224:225], off
	s_mov_b32 m0, s18
	s_nop 0
	global_load_lds_dwordx4 v[226:227], off
	s_waitcnt vmcnt(8)
	s_waitcnt lgkmcnt(0)
	s_barrier
; #define PG8_STAGE(bufoff, gbase, voff) do { _Pragma("unroll") for (int _i = 0; _i < 2; ++_i) \
;         __builtin_amdgcn_global_load_lds((const unsigned*)((const char*)(gbase) + (voff)[_i]), (PG8_LAS unsigned*)(lds + (bufoff) + ldsw + _i * 8192), 16, 0, 0); } while (0)
; #define PG8_LDA(dst, b, h) do { _Pragma("unroll") for (int m = 0; m < 4; ++m) _Pragma("unroll") for (int k = 0; k < 2; ++k) dst[m][k] = *(const PG8_LAS bf16x8*)(lds + PG8_SA(b, h) + aoff + m * 2048 + k * 1024); } while (0)
; #define PG8_LDB(dst, b, h) do { _Pragma("unroll") for (int n = 0; n < 2; ++n) _Pragma("unroll") for (int k = 0; k < 2; ++k) dst[n][k] = *(const PG8_LAS bf16x8*)(lds + PG8_SB(b, h) + boff + n * 2048 + k * 1024); } while (0)
; #define PG8_MMA(ai, bj, At, Bt) do { __builtin_amdgcn_s_setprio(1); _Pragma("unroll") for (int m = 0; m < 4; ++m) _Pragma("unroll") for (int n = 0; n < 2; ++n) _Pragma("unroll") for (int k = 0; k < 2; ++k) \
;         acc[ai][bj][m][n] = __builtin_amdgcn_mfma_f32_16x16x32_bf16(Bt[n][k], At[m][k], acc[ai][bj][m][n], 0, 0, 0); __builtin_amdgcn_s_setprio(0); } while (0)
; #define PG8_WAIT_V(n) asm volatile("s_waitcnt vmcnt(" #n ")" ::: "memory")
; #define PG8_WAIT_L(n) asm volatile("s_waitcnt lgkmcnt(" #n ")" ::: "memory")
; #define PG8_BAR __builtin_amdgcn_s_barrier()
; #define PG8_SCHED __builtin_amdgcn_sched_barrier(0)
; template <class Epi, class Sched, bool ALIGN_EPI = false, bool SP2 = false>
; __device__ __forceinline__ void gemm_phase(PG8_LAS unsigned char* lds, const Gemm g, const Sched& S, const Epi& E) {
;     ...
;             PG8_WAIT_V(8); PG8_WAIT_L(0); PG8_BAR; PG8_MMA(1, 0, At, B0); PG8_MMA(1, 1, At, B1); PG8_BAR; PG8_SCHED;
;             PG8_LDB(B0, 1, 0); PG8_LDB(B1, 1, 1); PG8_SCHED; PG8_LDA(At, 1, 0); PG8_STAGE(PG8_SA(0, 1), a2 + hstep, voffA);
;             PG8_WAIT_V(8); PG8_WAIT_L(0); PG8_BAR; PG8_MMA(0, 0, At, B0); PG8_MMA(0, 1, At, B1); PG8_BAR; PG8_SCHED;
	s_setprio 1
	s_waitcnt lgkmcnt(0)
	v_mfma_f32_16x16x32_bf16 v[60:63], v[128:131], v[176:179], 0
	v_mfma_f32_16x16x32_bf16 v[56:59], v[152:155], v[176:179], 0
	v_mfma_f32_16x16x32_bf16 v[44:47], v[128:131], v[184:187], 0
	v_mfma_f32_16x16x32_bf16 v[40:43], v[152:155], v[184:187], 0
	v_mfma_f32_16x16x32_bf16 v[28:31], v[128:131], v[192:195], 0
	v_mfma_f32_16x16x32_bf16 v[24:27], v[152:155], v[192:195], 0
	v_mfma_f32_16x16x32_bf16 v[12:15], v[128:131], v[212:215], 0
	v_mfma_f32_16x16x32_bf16 v[8:11], v[152:155], v[212:215], 0
	v_mfma_f32_16x16x32_bf16 v[60:63], v[132:135], v[180:183], v[60:63]
	v_mfma_f32_16x16x32_bf16 v[56:59], v[156:159], v[180:183], v[56:59]
	v_mfma_f32_16x16x32_bf16 v[44:47], v[132:135], v[188:191], v[44:47]
	v_mfma_f32_16x16x32_bf16 v[40:43], v[156:159], v[188:191], v[40:43]
	v_mfma_f32_16x16x32_bf16 v[28:31], v[132:135], v[208:211], v[28:31]
	v_mfma_f32_16x16x32_bf16 v[24:27], v[156:159], v[208:211], v[24:27]
	v_mfma_f32_16x16x32_bf16 v[12:15], v[132:135], v[216:219], v[12:15]
	v_mfma_f32_16x16x32_bf16 v[8:11], v[156:159], v[216:219], v[8:11]
	s_setprio 0
	s_setprio 1
	v_mfma_f32_16x16x32_bf16 v[52:55], v[160:163], v[176:179], 0
	v_mfma_f32_16x16x32_bf16 v[48:51], v[168:171], v[176:179], 0
	v_mfma_f32_16x16x32_bf16 v[36:39], v[160:163], v[184:187], 0
	v_mfma_f32_16x16x32_bf16 v[32:35], v[168:171], v[184:187], 0
	v_mfma_f32_16x16x32_bf16 v[20:23], v[160:163], v[192:195], 0
	v_mfma_f32_16x16x32_bf16 v[16:19], v[168:171], v[192:195], 0
	v_mfma_f32_16x16x32_bf16 v[4:7], v[160:163], v[212:215], 0
	v_mfma_f32_16x16x32_bf16 v[0:3], v[168:171], v[212:215], 0
	v_mfma_f32_16x16x32_bf16 v[52:55], v[164:167], v[180:183], v[52:55]
	v_mfma_f32_16x16x32_bf16 v[48:51], v[172:175], v[180:183], v[48:51]
	v_mfma_f32_16x16x32_bf16 v[36:39], v[164:167], v[188:191], v[36:39]
	v_mfma_f32_16x16x32_bf16 v[32:35], v[172:175], v[188:191], v[32:35]
	v_mfma_f32_16x16x32_bf16 v[20:23], v[164:167], v[208:211], v[20:23]
	v_mfma_f32_16x16x32_bf16 v[16:19], v[172:175], v[208:211], v[16:19]
	v_mfma_f32_16x16x32_bf16 v[4:7], v[164:167], v[216:219], v[4:7]
	v_mfma_f32_16x16x32_bf16 v[0:3], v[172:175], v[216:219], v[0:3]
	s_setprio 0
	s_barrier
	s_add_i32 s17, 0, 0x18000
	s_add_i32 s19, 0, 0x1c000
	v_add_u32_e32 v156, s17, v197
	v_add_u32_e32 v172, s19, v197
	ds_read_b128 v[128:131], v156
	ds_read_b128 v[132:135], v156 offset:1024
	ds_read_b128 v[152:155], v156 offset:2048
	ds_read_b128 v[156:159], v156 offset:3072
	ds_read_b128 v[160:163], v172
	ds_read_b128 v[164:167], v172 offset:1024
	ds_read_b128 v[168:171], v172 offset:2048
	ds_read_b128 v[172:175], v172 offset:3072
	s_add_u32 s8, s8, 0xb0000
	s_addc_u32 s9, s9, 0
	s_mov_b32 m0, s23
	v_lshl_add_u64 v[228:229], s[8:9], 0, v[136:137]
	ds_read_b128 v[176:179], v201 offset:32768
	ds_read_b128 v[180:183], v201 offset:33792
	ds_read_b128 v[184:187], v201 offset:34816
	ds_read_b128 v[188:191], v201 offset:35840
	ds_read_b128 v[192:195], v201 offset:36864
	ds_read_b128 v[208:211], v201 offset:37888
	ds_read_b128 v[212:215], v201 offset:38912
	ds_read_b128 v[216:219], v201 offset:39936
	global_load_lds_dwordx4 v[228:229], off
	v_lshl_add_u64 v[228:229], s[8:9], 0, v[140:141]
	s_mov_b32 m0, s33
	s_nop 0
	global_load_lds_dwordx4 v[228:229], off
	s_waitcnt vmcnt(8)
	s_waitcnt lgkmcnt(0)
	s_barrier
	s_setprio 1
	s_waitcnt lgkmcnt(0)
	v_mfma_f32_16x16x32_bf16 v[124:127], v[128:131], v[176:179], v[124:127]
	v_mfma_f32_16x16x32_bf16 v[120:123], v[152:155], v[176:179], v[120:123]
	v_mfma_f32_16x16x32_bf16 v[108:111], v[128:131], v[184:187], v[108:111]
	v_mfma_f32_16x16x32_bf16 v[104:107], v[152:155], v[184:187], v[104:107]
	v_mfma_f32_16x16x32_bf16 v[92:95], v[128:131], v[192:195], v[92:95]
	v_mfma_f32_16x16x32_bf16 v[88:91], v[152:155], v[192:195], v[88:91]
	v_mfma_f32_16x16x32_bf16 v[76:79], v[128:131], v[212:215], v[76:79]
	v_mfma_f32_16x16x32_bf16 v[72:75], v[152:155], v[212:215], v[72:75]
	v_mfma_f32_16x16x32_bf16 v[124:127], v[132:135], v[180:183], v[124:127]
	v_mfma_f32_16x16x32_bf16 v[120:123], v[156:159], v[180:183], v[120:123]
	v_mfma_f32_16x16x32_bf16 v[108:111], v[132:135], v[188:191], v[108:111]
	v_mfma_f32_16x16x32_bf16 v[104:107], v[156:159], v[188:191], v[104:107]
	v_mfma_f32_16x16x32_bf16 v[92:95], v[132:135], v[208:211], v[92:95]
	v_mfma_f32_16x16x32_bf16 v[88:91], v[156:159], v[208:211], v[88:91]
	v_mfma_f32_16x16x32_bf16 v[76:79], v[132:135], v[216:219], v[76:79]
	v_mfma_f32_16x16x32_bf16 v[72:75], v[156:159], v[216:219], v[72:75]
	s_setprio 0
	s_setprio 1
	v_mfma_f32_16x16x32_bf16 v[116:119], v[160:163], v[176:179], v[116:119]
	v_mfma_f32_16x16x32_bf16 v[112:115], v[168:171], v[176:179], v[112:115]
	v_mfma_f32_16x16x32_bf16 v[100:103], v[160:163], v[184:187], v[100:103]
	v_mfma_f32_16x16x32_bf16 v[96:99], v[168:171], v[184:187], v[96:99]
	v_mfma_f32_16x16x32_bf16 v[84:87], v[160:163], v[192:195], v[84:87]
	v_mfma_f32_16x16x32_bf16 v[80:83], v[168:171], v[192:195], v[80:83]
	v_mfma_f32_16x16x32_bf16 v[68:71], v[160:163], v[212:215], v[68:71]
	v_mfma_f32_16x16x32_bf16 v[64:67], v[168:171], v[212:215], v[64:67]
	v_mfma_f32_16x16x32_bf16 v[116:119], v[164:167], v[180:183], v[116:119]
	v_mfma_f32_16x16x32_bf16 v[112:115], v[172:175], v[180:183], v[112:115]
	v_mfma_f32_16x16x32_bf16 v[100:103], v[164:167], v[188:191], v[100:103]
	v_mfma_f32_16x16x32_bf16 v[96:99], v[172:175], v[188:191], v[96:99]
	v_mfma_f32_16x16x32_bf16 v[84:87], v[164:167], v[208:211], v[84:87]
	v_mfma_f32_16x16x32_bf16 v[80:83], v[172:175], v[208:211], v[80:83]
	v_mfma_f32_16x16x32_bf16 v[68:71], v[164:167], v[216:219], v[68:71]
	v_mfma_f32_16x16x32_bf16 v[64:67], v[172:175], v[216:219], v[64:67]
	s_setprio 0
	s_barrier
; #define PG8_STAGE(bufoff, gbase, voff) do { _Pragma("unroll") for (int _i = 0; _i < 2; ++_i) \
;         __builtin_amdgcn_global_load_lds((const unsigned*)((const char*)(gbase) + (voff)[_i]), (PG8_LAS unsigned*)(lds + (bufoff) + ldsw + _i * 8192), 16, 0, 0); } while (0)
; #define PG8_LDA(dst, b, h) do { _Pragma("unroll") for (int m = 0; m < 4; ++m) _Pragma("unroll") for (int k = 0; k < 2; ++k) dst[m][k] = *(const PG8_LAS bf16x8*)(lds + PG8_SA(b, h) + aoff + m * 2048 + k * 1024); } while (0)
; #define PG8_MMA(ai, bj, At, Bt) do { __builtin_amdgcn_s_setprio(1); _Pragma("unroll") for (int m = 0; m < 4; ++m) _Pragma("unroll") for (int n = 0; n < 2; ++n) _Pragma("unroll") for (int k = 0; k < 2; ++k) \
;         acc[ai][bj][m][n] = __builtin_amdgcn_mfma_f32_16x16x32_bf16(Bt[n][k], At[m][k], acc[ai][bj][m][n], 0, 0, 0); __builtin_amdgcn_s_setprio(0); } while (0)
; #define PG8_WAIT_V(n) asm volatile("s_waitcnt vmcnt(" #n ")" ::: "memory")
; #define PG8_WAIT_L(n) asm volatile("s_waitcnt lgkmcnt(" #n ")" ::: "memory")
; #define PG8_BAR __builtin_amdgcn_s_barrier()
; #define PG8_SCHED __builtin_amdgcn_sched_barrier(0)
; template <class Epi, class Sched, bool ALIGN_EPI = false, bool SP2 = false>
; __device__ __forceinline__ void gemm_phase(PG8_LAS unsigned char* lds, const Gemm g, const Sched& S, const Epi& E) {
;     ...
;         for (int t = 0; t < nt; t += 2) {
;             const bool last = (t == nt - 2);
;     ...
;             PG8_LDA(At, 1, 1); PG8_STAGE(PG8_SB(1, 0), b3, voffB); PG8_STAGE(PG8_SB(1, 1), b3 + hstep, voffB); PG8_STAGE(PG8_SA(1, 0), a3, voffA);
;             PG8_WAIT_V(8); PG8_WAIT_L(0); PG8_BAR; PG8_MMA(1, 0, At, B0); PG8_MMA(1, 1, At, B1); PG8_BAR; PG8_SCHED;
	s_add_i32 s8, s17, s14
	v_lshl_add_u64 v[220:221], v[220:221], 0, s[52:53]
	s_mov_b32 m0, s8
	ds_read_b128 v[176:179], v201 offset:49152
	ds_read_b128 v[180:183], v201 offset:50176
	ds_read_b128 v[184:187], v201 offset:51200
	ds_read_b128 v[188:191], v201 offset:52224
	ds_read_b128 v[192:195], v201 offset:53248
	ds_read_b128 v[208:211], v201 offset:54272
	ds_read_b128 v[212:215], v201 offset:55296
	ds_read_b128 v[216:219], v201 offset:56320
	global_load_lds_dwordx4 v[220:221], off
	s_add_i32 m0, s8, 0x2000
	s_add_u32 s6, s6, 0xb0080
	v_lshl_add_u64 v[220:221], v[222:223], 0, s[52:53]
	s_addc_u32 s7, s7, 0
	s_add_i32 s8, s19, s14
	global_load_lds_dwordx4 v[220:221], off
	v_lshl_add_u64 v[220:221], s[6:7], 0, v[138:139]
	s_mov_b32 m0, s8
	s_nop 0
	global_load_lds_dwordx4 v[220:221], off
	v_lshl_add_u64 v[220:221], s[6:7], 0, v[142:143]
	s_add_i32 m0, s8, 0x2000
	s_nop 0
	global_load_lds_dwordx4 v[220:221], off
	v_lshl_add_u64 v[220:221], v[224:225], 0, s[52:53]
	s_mov_b32 m0, s35
	s_nop 0
	global_load_lds_dwordx4 v[220:221], off
	v_lshl_add_u64 v[220:221], v[226:227], 0, s[52:53]
	s_mov_b32 m0, s62
	s_nop 0
	global_load_lds_dwordx4 v[220:221], off
	s_waitcnt vmcnt(8)
	s_waitcnt lgkmcnt(0)
	s_barrier
	s_setprio 1
	s_waitcnt lgkmcnt(0)
	v_mfma_f32_16x16x32_bf16 v[60:63], v[128:131], v[176:179], v[60:63]
	v_mfma_f32_16x16x32_bf16 v[56:59], v[152:155], v[176:179], v[56:59]
	v_mfma_f32_16x16x32_bf16 v[44:47], v[128:131], v[184:187], v[44:47]
	v_mfma_f32_16x16x32_bf16 v[40:43], v[152:155], v[184:187], v[40:43]
	v_mfma_f32_16x16x32_bf16 v[28:31], v[128:131], v[192:195], v[28:31]
	v_mfma_f32_16x16x32_bf16 v[24:27], v[152:155], v[192:195], v[24:27]
	v_mfma_f32_16x16x32_bf16 v[12:15], v[128:131], v[212:215], v[12:15]
	v_mfma_f32_16x16x32_bf16 v[8:11], v[152:155], v[212:215], v[8:11]
	v_mfma_f32_16x16x32_bf16 v[60:63], v[132:135], v[180:183], v[60:63]
	v_mfma_f32_16x16x32_bf16 v[56:59], v[156:159], v[180:183], v[56:59]
	v_mfma_f32_16x16x32_bf16 v[44:47], v[132:135], v[188:191], v[44:47]
	v_mfma_f32_16x16x32_bf16 v[40:43], v[156:159], v[188:191], v[40:43]
	v_mfma_f32_16x16x32_bf16 v[28:31], v[132:135], v[208:211], v[28:31]
	v_mfma_f32_16x16x32_bf16 v[24:27], v[156:159], v[208:211], v[24:27]
	v_mfma_f32_16x16x32_bf16 v[12:15], v[132:135], v[216:219], v[12:15]
	v_mfma_f32_16x16x32_bf16 v[8:11], v[156:159], v[216:219], v[8:11]
	s_setprio 0
	s_setprio 1
	v_mfma_f32_16x16x32_bf16 v[52:55], v[160:163], v[176:179], v[52:55]
	v_mfma_f32_16x16x32_bf16 v[48:51], v[168:171], v[176:179], v[48:51]
	v_mfma_f32_16x16x32_bf16 v[36:39], v[160:163], v[184:187], v[36:39]
	v_mfma_f32_16x16x32_bf16 v[32:35], v[168:171], v[184:187], v[32:35]
	v_mfma_f32_16x16x32_bf16 v[20:23], v[160:163], v[192:195], v[20:23]
	v_mfma_f32_16x16x32_bf16 v[16:19], v[168:171], v[192:195], v[16:19]
	v_mfma_f32_16x16x32_bf16 v[4:7], v[160:163], v[212:215], v[4:7]
	v_mfma_f32_16x16x32_bf16 v[0:3], v[168:171], v[212:215], v[0:3]
	v_mfma_f32_16x16x32_bf16 v[52:55], v[164:167], v[180:183], v[52:55]
	v_mfma_f32_16x16x32_bf16 v[48:51], v[172:175], v[180:183], v[48:51]
	v_mfma_f32_16x16x32_bf16 v[36:39], v[164:167], v[188:191], v[36:39]
	v_mfma_f32_16x16x32_bf16 v[32:35], v[172:175], v[188:191], v[32:35]
	v_mfma_f32_16x16x32_bf16 v[20:23], v[164:167], v[208:211], v[20:23]
	v_mfma_f32_16x16x32_bf16 v[16:19], v[172:175], v[208:211], v[16:19]
	v_mfma_f32_16x16x32_bf16 v[4:7], v[164:167], v[216:219], v[4:7]
	v_mfma_f32_16x16x32_bf16 v[0:3], v[172:175], v[216:219], v[0:3]
	s_setprio 0
	s_barrier
	s_add_i32 s16, s16, 2
	s_add_u32 s0, s0, 0x100
	s_addc_u32 s1, s1, 0
	s_add_u32 s12, s12, 0x100
	s_addc_u32 s13, s13, 0
	s_cmp_gt_u32 s16, 41
	s_cbranch_scc1 .Lpeel_exit_4

; #define PG8_BAR __builtin_amdgcn_s_barrier()
; template <class Epi, class Sched, bool ALIGN_EPI = false, bool SP2 = false>
; __device__ __forceinline__ void gemm_phase(PG8_LAS unsigned char* lds, const Gemm g, const Sched& S, const Epi& E) {
;     ...
;         if constexpr (ALIGN_EPI) { if (wr == 0) PG8_BAR; }
.Lpeel_exit_4:
	s_and_b64 vcc, exec, s[54:55]
	s_cbranch_vccz .LBB0_686
	s_barrier
